# evin_odin
# speedup vs baseline: 1.0233x; 1.0006x over previous
; template <int EPI>
; __device__ __forceinline__ void gemm_epi(const GemmArgs& G, const f32x4 (&a)[4][2], int rbase, int cbase, int fq, const float (&ssv)[4]) {
;   const int tn = cbase >> 8;
; #pragma unroll
;   for (int m = 0; m < 4; ++m) {
;     const int row = rbase + m * 16;
;     float rs = 1.f;
;     if constexpr (EPI == EPI_GU || EPI == EPI_EVIN || EPI == EPI_ODIN) rs = rsqrtf(ssv[m] * (1.f / 2048.f) + 1e-6f);
;     if constexpr (EPI == EPI_GU) {
;       const f32x4 gv = a[m][0] * rs, uv = a[m][1] * rs;
;       const int hc = (cbase >> 1) + fq * 4;
;       u32x2 o = {cvtpk(silu_f(gv[0]) * uv[0], silu_f(gv[1]) * uv[1]), cvtpk(silu_f(gv[2]) * uv[2], silu_f(gv[3]) * uv[3])};
;       *reinterpret_cast<u32x2*>(G.d0 + (size_t)(row - G.row0) * DFF + hc) = o;
;     } else {
; #pragma unroll
;       for (int n = 0; n < 2; ++n) {
;         const f32x4 v = a[m][n] * rs;
;         const int col = cbase + n * 16 + fq * 4;
;         if constexpr (EPI == EPI_POOL) {
;           const int cg_ = G.aux * 256 + col;
;           f32x4 sc = *reinterpret_cast<const f32x4*>(G.c0 + cg_);
;           u32x2 o = {cvtpk(v[0] * sc[0], v[1] * sc[1]), cvtpk(v[2] * sc[2], v[3] * sc[3])};
;           *reinterpret_cast<u32x2*>(G.d0 + (size_t)row * 1024 + cg_) = o;
;         } else if constexpr (EPI == EPI_EVIN) {
;           u32x2 o = {cvtpk(v[0], v[1]), cvtpk(v[2], v[3])};
;           u16* dp;
;           if (tn < 4) dp = G.d0 + (size_t)row * 1024 + col;
;           else if (tn < 8) dp = G.d1 + (size_t)row * 1024 + (col - 1024);
;           else if (tn == 8) dp = G.d2 + (size_t)row * 256 + (col - 2048);
;           else dp = G.d3 + (size_t)row * 256 + (col - 2304);
;           *reinterpret_cast<u32x2*>(dp) = o;
;         } else {
;           if (tn < 16) {
;             u32x2 o = {cvtpk(v[0], v[1]), cvtpk(v[2], v[3])};
;             u16* dp;
;             if (tn < 4) dp = G.d0 + (size_t)row * 1024 + col;
;             else if (tn == 4) dp = G.d1 + (size_t)row * 256 + (col - 1024);
;             else if (tn == 5) dp = G.d2 + (size_t)row * 256 + (col - 1280);
;             else if (tn < 10) dp = G.d3 + (size_t)row * 1024 + (col - 1536);
;             else dp = G.d4 + (size_t)row * 1536 + (col - 2560);
;             *reinterpret_cast<u32x2*>(dp) = o;
.LBB0_751:
	s_lshr_b32 s6, s36, 8
	s_cmp_eq_u32 s6, 16
	s_cbranch_scc1 .Lmy_od_old
	v_readfirstlane_b32 s7, v224
	s_andn2_b32 s7, s7, 63
	s_nop 0
	v_add_u32_e32 v128, s7, v225
	v_and_b32_e32 v129, 15, v128
	v_ashrrev_i32_e32 v131, 2, v128
	v_and_or_b32 v129, v131, 64, v129
	v_lshrrev_b32_e32 v131, 1, v128
	v_and_b32_e32 v131, 0x60, v131
	v_lshrrev_b32_e32 v128, 2, v128
	v_and_or_b32 v131, v128, 12, v131
	v_add_u32_e32 v129, s40, v129
	v_add_u32_e32 v131, s36, v131
	v_mov_b32_e32 v249, v245
	s_waitcnt vmcnt(8)
	v_fmamk_f32 v158, v130, 0x3a000000, v229
	v_fmamk_f32 v160, v146, 0x3a000000, v229
	v_fmamk_f32 v162, v148, 0x3a000000, v229
	v_fmamk_f32 v164, v156, 0x3a000000, v229
	v_fmamk_f32 v166, v154, 0x3a000000, v229
	v_fmamk_f32 v168, v153, 0x3a000000, v229
	v_fmamk_f32 v170, v152, 0x3a000000, v229
	v_fmamk_f32 v172, v150, 0x3a000000, v229
	v_rsq_f32_e32 v158, v158
	v_rsq_f32_e32 v160, v160
	v_rsq_f32_e32 v162, v162
	v_rsq_f32_e32 v164, v164
	v_rsq_f32_e32 v166, v166
	v_rsq_f32_e32 v168, v168
	v_rsq_f32_e32 v170, v170
	v_rsq_f32_e32 v172, v172
	s_mov_b64 s[8:9], s[18:19]
	s_mov_b32 s7, 0
	s_cmp_lt_u32 s6, 4
	s_cbranch_scc1 .Lmy_od_p11
	s_mov_b64 s[8:9], s[20:21]
	s_movk_i32 s7, 0xf800
	s_cmp_eq_u32 s6, 4
	s_cbranch_scc1 .Lmy_od_p9
	s_cmp_eq_u32 s6, 5
	s_cbranch_scc0 .Lmy_od_sel3
	v_readlane_b32 s8, v254, 9
	v_readlane_b32 s9, v254, 10
	s_movk_i32 s7, 0xf600
	s_branch .Lmy_od_p9
.Lmy_od_sel3:
	s_cmp_lt_u32 s6, 10
	s_cbranch_scc0 .Lmy_od_sel4
	v_readlane_b32 s8, v254, 11
	v_readlane_b32 s9, v254, 12
	s_movk_i32 s7, 0xf400
	s_branch .Lmy_od_p11
.Lmy_od_sel4:
	s_mov_b64 s[8:9], s[26:27]
	s_movk_i32 s7, 0xec00
.Lmy_od_pmul:
	v_mul_u32_u24_e32 v132, 0xc00, v129
	v_lshl_add_u32 v132, v131, 1, v132
	v_add_u32_e32 v132, s7, v132
	s_nop 1
	v_pk_mul_f32 v[124:125], v[158:159], v[124:125] op_sel_hi:[0,1]
	v_pk_mul_f32 v[120:121], v[158:159], v[120:121] op_sel_hi:[0,1]
	v_pk_mul_f32 v[126:127], v[158:159], v[126:127] op_sel_hi:[0,1]
	v_pk_mul_f32 v[122:123], v[158:159], v[122:123] op_sel_hi:[0,1]
	v_cvt_pk_bf16_f32 v174, v124, v125
	v_cvt_pk_bf16_f32 v176, v120, v121
	v_cvt_pk_bf16_f32 v175, v126, v127
	v_cvt_pk_bf16_f32 v177, v122, v123
	v_mov_b32_e32 v182, v132
	v_add_u32_e32 v183, 0x20, v132
	global_store_dwordx2 v182, v[174:175], s[8:9]
	global_store_dwordx2 v183, v[176:177], s[8:9]
	v_pk_mul_f32 v[116:117], v[160:161], v[116:117] op_sel_hi:[0,1]
	v_pk_mul_f32 v[112:113], v[160:161], v[112:113] op_sel_hi:[0,1]
	v_pk_mul_f32 v[118:119], v[160:161], v[118:119] op_sel_hi:[0,1]
	v_pk_mul_f32 v[114:115], v[160:161], v[114:115] op_sel_hi:[0,1]
	v_cvt_pk_bf16_f32 v178, v116, v117
	v_cvt_pk_bf16_f32 v186, v112, v113
	v_cvt_pk_bf16_f32 v179, v118, v119
	v_cvt_pk_bf16_f32 v187, v114, v115
	v_add_u32_e32 v184, 0xc000, v132
	v_add_u32_e32 v185, 0xc020, v132
	global_store_dwordx2 v184, v[178:179], s[8:9]
	global_store_dwordx2 v185, v[186:187], s[8:9]
	v_pk_mul_f32 v[108:109], v[162:163], v[108:109] op_sel_hi:[0,1]
	v_pk_mul_f32 v[104:105], v[162:163], v[104:105] op_sel_hi:[0,1]
	v_pk_mul_f32 v[110:111], v[162:163], v[110:111] op_sel_hi:[0,1]
	v_pk_mul_f32 v[106:107], v[162:163], v[106:107] op_sel_hi:[0,1]
	v_cvt_pk_bf16_f32 v174, v108, v109
	v_cvt_pk_bf16_f32 v176, v104, v105
	v_cvt_pk_bf16_f32 v175, v110, v111
	v_cvt_pk_bf16_f32 v177, v106, v107
	v_add_u32_e32 v182, 0x18000, v132
	v_add_u32_e32 v183, 0x18020, v132
	global_store_dwordx2 v182, v[174:175], s[8:9]
	global_store_dwordx2 v183, v[176:177], s[8:9]
	v_pk_mul_f32 v[100:101], v[164:165], v[100:101] op_sel_hi:[0,1]
	v_pk_mul_f32 v[96:97], v[164:165], v[96:97] op_sel_hi:[0,1]
	v_pk_mul_f32 v[102:103], v[164:165], v[102:103] op_sel_hi:[0,1]
	v_pk_mul_f32 v[98:99], v[164:165], v[98:99] op_sel_hi:[0,1]
	v_cvt_pk_bf16_f32 v178, v100, v101
	v_cvt_pk_bf16_f32 v186, v96, v97
	v_cvt_pk_bf16_f32 v179, v102, v103
	v_cvt_pk_bf16_f32 v187, v98, v99
	v_add_u32_e32 v184, 0x24000, v132
	v_add_u32_e32 v185, 0x24020, v132
	global_store_dwordx2 v184, v[178:179], s[8:9]
	global_store_dwordx2 v185, v[186:187], s[8:9]
	v_pk_mul_f32 v[92:93], v[158:159], v[92:93] op_sel_hi:[0,1]
	v_pk_mul_f32 v[88:89], v[158:159], v[88:89] op_sel_hi:[0,1]
	v_pk_mul_f32 v[94:95], v[158:159], v[94:95] op_sel_hi:[0,1]
	v_pk_mul_f32 v[90:91], v[158:159], v[90:91] op_sel_hi:[0,1]
	v_cvt_pk_bf16_f32 v174, v92, v93
	v_cvt_pk_bf16_f32 v176, v88, v89
	v_cvt_pk_bf16_f32 v175, v94, v95
	v_cvt_pk_bf16_f32 v177, v90, v91
	v_add_u32_e32 v182, 0x100, v132
	v_add_u32_e32 v183, 0x120, v132
	global_store_dwordx2 v182, v[174:175], s[8:9]
	global_store_dwordx2 v183, v[176:177], s[8:9]
	v_pk_mul_f32 v[84:85], v[160:161], v[84:85] op_sel_hi:[0,1]
	v_pk_mul_f32 v[80:81], v[160:161], v[80:81] op_sel_hi:[0,1]
	v_pk_mul_f32 v[86:87], v[160:161], v[86:87] op_sel_hi:[0,1]
	v_pk_mul_f32 v[82:83], v[160:161], v[82:83] op_sel_hi:[0,1]
	v_cvt_pk_bf16_f32 v178, v84, v85
	v_cvt_pk_bf16_f32 v186, v80, v81
	v_cvt_pk_bf16_f32 v179, v86, v87
	v_cvt_pk_bf16_f32 v187, v82, v83
	v_add_u32_e32 v184, 0xc100, v132
	v_add_u32_e32 v185, 0xc120, v132
	global_store_dwordx2 v184, v[178:179], s[8:9]
	global_store_dwordx2 v185, v[186:187], s[8:9]
	v_pk_mul_f32 v[76:77], v[162:163], v[76:77] op_sel_hi:[0,1]
	v_pk_mul_f32 v[72:73], v[162:163], v[72:73] op_sel_hi:[0,1]
	v_pk_mul_f32 v[78:79], v[162:163], v[78:79] op_sel_hi:[0,1]
	v_pk_mul_f32 v[74:75], v[162:163], v[74:75] op_sel_hi:[0,1]
	v_cvt_pk_bf16_f32 v174, v76, v77
	v_cvt_pk_bf16_f32 v176, v72, v73
	v_cvt_pk_bf16_f32 v175, v78, v79
	v_cvt_pk_bf16_f32 v177, v74, v75
	v_add_u32_e32 v182, 0x18100, v132
	v_add_u32_e32 v183, 0x18120, v132
	global_store_dwordx2 v182, v[174:175], s[8:9]
	global_store_dwordx2 v183, v[176:177], s[8:9]
; template <int EPI>
; __device__ __forceinline__ void gemm_epi(const GemmArgs& G, const f32x4 (&a)[4][2], int rbase, int cbase, int fq, const float (&ssv)[4]) {
;   const int tn = cbase >> 8;
; #pragma unroll
;   for (int m = 0; m < 4; ++m) {
;     const int row = rbase + m * 16;
;     float rs = 1.f;
;     if constexpr (EPI == EPI_GU || EPI == EPI_EVIN || EPI == EPI_ODIN) rs = rsqrtf(ssv[m] * (1.f / 2048.f) + 1e-6f);
;     if constexpr (EPI == EPI_GU) {
;       const f32x4 gv = a[m][0] * rs, uv = a[m][1] * rs;
;       const int hc = (cbase >> 1) + fq * 4;
;       u32x2 o = {cvtpk(silu_f(gv[0]) * uv[0], silu_f(gv[1]) * uv[1]), cvtpk(silu_f(gv[2]) * uv[2], silu_f(gv[3]) * uv[3])};
;       *reinterpret_cast<u32x2*>(G.d0 + (size_t)(row - G.row0) * DFF + hc) = o;
;     } else {
; #pragma unroll
;       for (int n = 0; n < 2; ++n) {
;         const f32x4 v = a[m][n] * rs;
;         const int col = cbase + n * 16 + fq * 4;
;         if constexpr (EPI == EPI_POOL) {
;           const int cg_ = G.aux * 256 + col;
;           f32x4 sc = *reinterpret_cast<const f32x4*>(G.c0 + cg_);
;           u32x2 o = {cvtpk(v[0] * sc[0], v[1] * sc[1]), cvtpk(v[2] * sc[2], v[3] * sc[3])};
;           *reinterpret_cast<u32x2*>(G.d0 + (size_t)row * 1024 + cg_) = o;
;         } else if constexpr (EPI == EPI_EVIN) {
;           u32x2 o = {cvtpk(v[0], v[1]), cvtpk(v[2], v[3])};
;           u16* dp;
;           if (tn < 4) dp = G.d0 + (size_t)row * 1024 + col;
;           else if (tn < 8) dp = G.d1 + (size_t)row * 1024 + (col - 1024);
;           else if (tn == 8) dp = G.d2 + (size_t)row * 256 + (col - 2048);
;           else dp = G.d3 + (size_t)row * 256 + (col - 2304);
;           *reinterpret_cast<u32x2*>(dp) = o;
;         } else {
;           if (tn < 16) {
;             u32x2 o = {cvtpk(v[0], v[1]), cvtpk(v[2], v[3])};
;             u16* dp;
;             if (tn < 4) dp = G.d0 + (size_t)row * 1024 + col;
;             else if (tn == 4) dp = G.d1 + (size_t)row * 256 + (col - 1024);
;             else if (tn == 5) dp = G.d2 + (size_t)row * 256 + (col - 1280);
;             else if (tn < 10) dp = G.d3 + (size_t)row * 1024 + (col - 1536);
;             else dp = G.d4 + (size_t)row * 1536 + (col - 2560);
;             *reinterpret_cast<u32x2*>(dp) = o;
	v_pk_mul_f32 v[68:69], v[164:165], v[68:69] op_sel_hi:[0,1]
	v_pk_mul_f32 v[64:65], v[164:165], v[64:65] op_sel_hi:[0,1]
	v_pk_mul_f32 v[70:71], v[164:165], v[70:71] op_sel_hi:[0,1]
	v_pk_mul_f32 v[66:67], v[164:165], v[66:67] op_sel_hi:[0,1]
	v_cvt_pk_bf16_f32 v178, v68, v69
	v_cvt_pk_bf16_f32 v186, v64, v65
	v_cvt_pk_bf16_f32 v179, v70, v71
	v_cvt_pk_bf16_f32 v187, v66, v67
	v_add_u32_e32 v184, 0x24100, v132
	v_add_u32_e32 v185, 0x24120, v132
	global_store_dwordx2 v184, v[178:179], s[8:9]
	global_store_dwordx2 v185, v[186:187], s[8:9]
	v_pk_mul_f32 v[60:61], v[166:167], v[60:61] op_sel_hi:[0,1]
	v_pk_mul_f32 v[56:57], v[166:167], v[56:57] op_sel_hi:[0,1]
	v_pk_mul_f32 v[62:63], v[166:167], v[62:63] op_sel_hi:[0,1]
	v_pk_mul_f32 v[58:59], v[166:167], v[58:59] op_sel_hi:[0,1]
	v_cvt_pk_bf16_f32 v174, v60, v61
	v_cvt_pk_bf16_f32 v176, v56, v57
	v_cvt_pk_bf16_f32 v175, v62, v63
	v_cvt_pk_bf16_f32 v177, v58, v59
	v_add_u32_e32 v182, 0x60000, v132
	v_add_u32_e32 v183, 0x60020, v132
	global_store_dwordx2 v182, v[174:175], s[8:9]
	global_store_dwordx2 v183, v[176:177], s[8:9]
	v_pk_mul_f32 v[52:53], v[168:169], v[52:53] op_sel_hi:[0,1]
	v_pk_mul_f32 v[48:49], v[168:169], v[48:49] op_sel_hi:[0,1]
	v_pk_mul_f32 v[54:55], v[168:169], v[54:55] op_sel_hi:[0,1]
	v_pk_mul_f32 v[50:51], v[168:169], v[50:51] op_sel_hi:[0,1]
	v_cvt_pk_bf16_f32 v178, v52, v53
	v_cvt_pk_bf16_f32 v186, v48, v49
	v_cvt_pk_bf16_f32 v179, v54, v55
	v_cvt_pk_bf16_f32 v187, v50, v51
	v_add_u32_e32 v184, 0x6c000, v132
	v_add_u32_e32 v185, 0x6c020, v132
	global_store_dwordx2 v184, v[178:179], s[8:9]
	global_store_dwordx2 v185, v[186:187], s[8:9]
	v_pk_mul_f32 v[44:45], v[170:171], v[44:45] op_sel_hi:[0,1]
	v_pk_mul_f32 v[40:41], v[170:171], v[40:41] op_sel_hi:[0,1]
	v_pk_mul_f32 v[46:47], v[170:171], v[46:47] op_sel_hi:[0,1]
	v_pk_mul_f32 v[42:43], v[170:171], v[42:43] op_sel_hi:[0,1]
	v_cvt_pk_bf16_f32 v174, v44, v45
	v_cvt_pk_bf16_f32 v176, v40, v41
	v_cvt_pk_bf16_f32 v175, v46, v47
	v_cvt_pk_bf16_f32 v177, v42, v43
	v_add_u32_e32 v182, 0x78000, v132
	v_add_u32_e32 v183, 0x78020, v132
	global_store_dwordx2 v182, v[174:175], s[8:9]
	global_store_dwordx2 v183, v[176:177], s[8:9]
	v_pk_mul_f32 v[36:37], v[172:173], v[36:37] op_sel_hi:[0,1]
	v_pk_mul_f32 v[32:33], v[172:173], v[32:33] op_sel_hi:[0,1]
	v_pk_mul_f32 v[38:39], v[172:173], v[38:39] op_sel_hi:[0,1]
	v_pk_mul_f32 v[34:35], v[172:173], v[34:35] op_sel_hi:[0,1]
	v_cvt_pk_bf16_f32 v178, v36, v37
	v_cvt_pk_bf16_f32 v186, v32, v33
	v_cvt_pk_bf16_f32 v179, v38, v39
	v_cvt_pk_bf16_f32 v187, v34, v35
	v_add_u32_e32 v184, 0x84000, v132
	v_add_u32_e32 v185, 0x84020, v132
	global_store_dwordx2 v184, v[178:179], s[8:9]
	global_store_dwordx2 v185, v[186:187], s[8:9]
	v_pk_mul_f32 v[28:29], v[166:167], v[28:29] op_sel_hi:[0,1]
	v_pk_mul_f32 v[24:25], v[166:167], v[24:25] op_sel_hi:[0,1]
	v_pk_mul_f32 v[30:31], v[166:167], v[30:31] op_sel_hi:[0,1]
	v_pk_mul_f32 v[26:27], v[166:167], v[26:27] op_sel_hi:[0,1]
	v_cvt_pk_bf16_f32 v174, v28, v29
	v_cvt_pk_bf16_f32 v176, v24, v25
	v_cvt_pk_bf16_f32 v175, v30, v31
	v_cvt_pk_bf16_f32 v177, v26, v27
	v_add_u32_e32 v182, 0x60100, v132
	v_add_u32_e32 v183, 0x60120, v132
	global_store_dwordx2 v182, v[174:175], s[8:9]
	global_store_dwordx2 v183, v[176:177], s[8:9]
	v_pk_mul_f32 v[20:21], v[168:169], v[20:21] op_sel_hi:[0,1]
	v_pk_mul_f32 v[16:17], v[168:169], v[16:17] op_sel_hi:[0,1]
	v_pk_mul_f32 v[22:23], v[168:169], v[22:23] op_sel_hi:[0,1]
	v_pk_mul_f32 v[18:19], v[168:169], v[18:19] op_sel_hi:[0,1]
	v_cvt_pk_bf16_f32 v178, v20, v21
	v_cvt_pk_bf16_f32 v186, v16, v17
	v_cvt_pk_bf16_f32 v179, v22, v23
	v_cvt_pk_bf16_f32 v187, v18, v19
	v_add_u32_e32 v184, 0x6c100, v132
	v_add_u32_e32 v185, 0x6c120, v132
	global_store_dwordx2 v184, v[178:179], s[8:9]
	global_store_dwordx2 v185, v[186:187], s[8:9]
	v_pk_mul_f32 v[12:13], v[170:171], v[12:13] op_sel_hi:[0,1]
	v_pk_mul_f32 v[8:9], v[170:171], v[8:9] op_sel_hi:[0,1]
	v_pk_mul_f32 v[14:15], v[170:171], v[14:15] op_sel_hi:[0,1]
	v_pk_mul_f32 v[10:11], v[170:171], v[10:11] op_sel_hi:[0,1]
	v_cvt_pk_bf16_f32 v174, v12, v13
	v_cvt_pk_bf16_f32 v176, v8, v9
	v_cvt_pk_bf16_f32 v175, v14, v15
	v_cvt_pk_bf16_f32 v177, v10, v11
	v_add_u32_e32 v182, 0x78100, v132
	v_add_u32_e32 v183, 0x78120, v132
	global_store_dwordx2 v182, v[174:175], s[8:9]
	global_store_dwordx2 v183, v[176:177], s[8:9]
	v_pk_mul_f32 v[4:5], v[172:173], v[4:5] op_sel_hi:[0,1]
	v_pk_mul_f32 v[0:1], v[172:173], v[0:1] op_sel_hi:[0,1]
	v_pk_mul_f32 v[6:7], v[172:173], v[6:7] op_sel_hi:[0,1]
	v_pk_mul_f32 v[2:3], v[172:173], v[2:3] op_sel_hi:[0,1]
	v_cvt_pk_bf16_f32 v178, v4, v5
	v_cvt_pk_bf16_f32 v186, v0, v1
	v_cvt_pk_bf16_f32 v179, v6, v7
	v_cvt_pk_bf16_f32 v187, v2, v3
	v_add_u32_e32 v184, 0x84100, v132
	v_add_u32_e32 v185, 0x84120, v132
	global_store_dwordx2 v184, v[178:179], s[8:9]
	global_store_dwordx2 v185, v[186:187], s[8:9]
	s_branch .LBB0_738
; template <int EPI>
; __device__ __forceinline__ void gemm_epi(const GemmArgs& G, const f32x4 (&a)[4][2], int rbase, int cbase, int fq, const float (&ssv)[4]) {
;   const int tn = cbase >> 8;
; #pragma unroll
;   for (int m = 0; m < 4; ++m) {
;     const int row = rbase + m * 16;
;     float rs = 1.f;
;     if constexpr (EPI == EPI_GU || EPI == EPI_EVIN || EPI == EPI_ODIN) rs = rsqrtf(ssv[m] * (1.f / 2048.f) + 1e-6f);
;     if constexpr (EPI == EPI_GU) {
;       const f32x4 gv = a[m][0] * rs, uv = a[m][1] * rs;
;       const int hc = (cbase >> 1) + fq * 4;
;       u32x2 o = {cvtpk(silu_f(gv[0]) * uv[0], silu_f(gv[1]) * uv[1]), cvtpk(silu_f(gv[2]) * uv[2], silu_f(gv[3]) * uv[3])};
;       *reinterpret_cast<u32x2*>(G.d0 + (size_t)(row - G.row0) * DFF + hc) = o;
;     } else {
; #pragma unroll
;       for (int n = 0; n < 2; ++n) {
;         const f32x4 v = a[m][n] * rs;
;         const int col = cbase + n * 16 + fq * 4;
;         if constexpr (EPI == EPI_POOL) {
;           const int cg_ = G.aux * 256 + col;
;           f32x4 sc = *reinterpret_cast<const f32x4*>(G.c0 + cg_);
;           u32x2 o = {cvtpk(v[0] * sc[0], v[1] * sc[1]), cvtpk(v[2] * sc[2], v[3] * sc[3])};
;           *reinterpret_cast<u32x2*>(G.d0 + (size_t)row * 1024 + cg_) = o;
;         } else if constexpr (EPI == EPI_EVIN) {
;           u32x2 o = {cvtpk(v[0], v[1]), cvtpk(v[2], v[3])};
;           u16* dp;
;           if (tn < 4) dp = G.d0 + (size_t)row * 1024 + col;
;           else if (tn < 8) dp = G.d1 + (size_t)row * 1024 + (col - 1024);
;           else if (tn == 8) dp = G.d2 + (size_t)row * 256 + (col - 2048);
;           else dp = G.d3 + (size_t)row * 256 + (col - 2304);
;           *reinterpret_cast<u32x2*>(dp) = o;
;         } else {
;           if (tn < 16) {
;             u32x2 o = {cvtpk(v[0], v[1]), cvtpk(v[2], v[3])};
;             u16* dp;
;             if (tn < 4) dp = G.d0 + (size_t)row * 1024 + col;
;             else if (tn == 4) dp = G.d1 + (size_t)row * 256 + (col - 1024);
;             else if (tn == 5) dp = G.d2 + (size_t)row * 256 + (col - 1280);
;             else if (tn < 10) dp = G.d3 + (size_t)row * 1024 + (col - 1536);
;             else dp = G.d4 + (size_t)row * 1536 + (col - 2560);
;             *reinterpret_cast<u32x2*>(dp) = o;
.Lmy_od_p9:
	v_lshlrev_b32_e32 v132, 9, v129
	v_lshl_add_u32 v132, v131, 1, v132
	v_add_u32_e32 v132, s7, v132
	s_nop 1
	v_pk_mul_f32 v[124:125], v[158:159], v[124:125] op_sel_hi:[0,1]
	v_pk_mul_f32 v[120:121], v[158:159], v[120:121] op_sel_hi:[0,1]
	v_pk_mul_f32 v[126:127], v[158:159], v[126:127] op_sel_hi:[0,1]
	v_pk_mul_f32 v[122:123], v[158:159], v[122:123] op_sel_hi:[0,1]
	v_cvt_pk_bf16_f32 v174, v124, v125
	v_cvt_pk_bf16_f32 v176, v120, v121
	v_cvt_pk_bf16_f32 v175, v126, v127
	v_cvt_pk_bf16_f32 v177, v122, v123
	v_mov_b32_e32 v182, v132
	v_add_u32_e32 v183, 0x20, v132
	global_store_dwordx2 v182, v[174:175], s[8:9]
	global_store_dwordx2 v183, v[176:177], s[8:9]
	v_pk_mul_f32 v[116:117], v[160:161], v[116:117] op_sel_hi:[0,1]
	v_pk_mul_f32 v[112:113], v[160:161], v[112:113] op_sel_hi:[0,1]
	v_pk_mul_f32 v[118:119], v[160:161], v[118:119] op_sel_hi:[0,1]
	v_pk_mul_f32 v[114:115], v[160:161], v[114:115] op_sel_hi:[0,1]
	v_cvt_pk_bf16_f32 v178, v116, v117
	v_cvt_pk_bf16_f32 v186, v112, v113
	v_cvt_pk_bf16_f32 v179, v118, v119
	v_cvt_pk_bf16_f32 v187, v114, v115
	v_add_u32_e32 v184, 0x2000, v132
	v_add_u32_e32 v185, 0x2020, v132
	global_store_dwordx2 v184, v[178:179], s[8:9]
	global_store_dwordx2 v185, v[186:187], s[8:9]
	v_pk_mul_f32 v[108:109], v[162:163], v[108:109] op_sel_hi:[0,1]
	v_pk_mul_f32 v[104:105], v[162:163], v[104:105] op_sel_hi:[0,1]
	v_pk_mul_f32 v[110:111], v[162:163], v[110:111] op_sel_hi:[0,1]
	v_pk_mul_f32 v[106:107], v[162:163], v[106:107] op_sel_hi:[0,1]
	v_cvt_pk_bf16_f32 v174, v108, v109
	v_cvt_pk_bf16_f32 v176, v104, v105
	v_cvt_pk_bf16_f32 v175, v110, v111
	v_cvt_pk_bf16_f32 v177, v106, v107
	v_add_u32_e32 v182, 0x4000, v132
	v_add_u32_e32 v183, 0x4020, v132
	global_store_dwordx2 v182, v[174:175], s[8:9]
	global_store_dwordx2 v183, v[176:177], s[8:9]
	v_pk_mul_f32 v[100:101], v[164:165], v[100:101] op_sel_hi:[0,1]
	v_pk_mul_f32 v[96:97], v[164:165], v[96:97] op_sel_hi:[0,1]
	v_pk_mul_f32 v[102:103], v[164:165], v[102:103] op_sel_hi:[0,1]
	v_pk_mul_f32 v[98:99], v[164:165], v[98:99] op_sel_hi:[0,1]
	v_cvt_pk_bf16_f32 v178, v100, v101
	v_cvt_pk_bf16_f32 v186, v96, v97
	v_cvt_pk_bf16_f32 v179, v102, v103
	v_cvt_pk_bf16_f32 v187, v98, v99
	v_add_u32_e32 v184, 0x6000, v132
	v_add_u32_e32 v185, 0x6020, v132
	global_store_dwordx2 v184, v[178:179], s[8:9]
	global_store_dwordx2 v185, v[186:187], s[8:9]
	v_pk_mul_f32 v[92:93], v[158:159], v[92:93] op_sel_hi:[0,1]
	v_pk_mul_f32 v[88:89], v[158:159], v[88:89] op_sel_hi:[0,1]
	v_pk_mul_f32 v[94:95], v[158:159], v[94:95] op_sel_hi:[0,1]
	v_pk_mul_f32 v[90:91], v[158:159], v[90:91] op_sel_hi:[0,1]
	v_cvt_pk_bf16_f32 v174, v92, v93
	v_cvt_pk_bf16_f32 v176, v88, v89
	v_cvt_pk_bf16_f32 v175, v94, v95
	v_cvt_pk_bf16_f32 v177, v90, v91
	v_add_u32_e32 v182, 0x100, v132
	v_add_u32_e32 v183, 0x120, v132
	global_store_dwordx2 v182, v[174:175], s[8:9]
	global_store_dwordx2 v183, v[176:177], s[8:9]
	v_pk_mul_f32 v[84:85], v[160:161], v[84:85] op_sel_hi:[0,1]
	v_pk_mul_f32 v[80:81], v[160:161], v[80:81] op_sel_hi:[0,1]
	v_pk_mul_f32 v[86:87], v[160:161], v[86:87] op_sel_hi:[0,1]
	v_pk_mul_f32 v[82:83], v[160:161], v[82:83] op_sel_hi:[0,1]
	v_cvt_pk_bf16_f32 v178, v84, v85
	v_cvt_pk_bf16_f32 v186, v80, v81
	v_cvt_pk_bf16_f32 v179, v86, v87
	v_cvt_pk_bf16_f32 v187, v82, v83
	v_add_u32_e32 v184, 0x2100, v132
	v_add_u32_e32 v185, 0x2120, v132
	global_store_dwordx2 v184, v[178:179], s[8:9]
	global_store_dwordx2 v185, v[186:187], s[8:9]
	v_pk_mul_f32 v[76:77], v[162:163], v[76:77] op_sel_hi:[0,1]
	v_pk_mul_f32 v[72:73], v[162:163], v[72:73] op_sel_hi:[0,1]
	v_pk_mul_f32 v[78:79], v[162:163], v[78:79] op_sel_hi:[0,1]
	v_pk_mul_f32 v[74:75], v[162:163], v[74:75] op_sel_hi:[0,1]
	v_cvt_pk_bf16_f32 v174, v76, v77
	v_cvt_pk_bf16_f32 v176, v72, v73
	v_cvt_pk_bf16_f32 v175, v78, v79
	v_cvt_pk_bf16_f32 v177, v74, v75
	v_add_u32_e32 v182, 0x4100, v132
	v_add_u32_e32 v183, 0x4120, v132
	global_store_dwordx2 v182, v[174:175], s[8:9]
	global_store_dwordx2 v183, v[176:177], s[8:9]
	v_pk_mul_f32 v[68:69], v[164:165], v[68:69] op_sel_hi:[0,1]
	v_pk_mul_f32 v[64:65], v[164:165], v[64:65] op_sel_hi:[0,1]
	v_pk_mul_f32 v[70:71], v[164:165], v[70:71] op_sel_hi:[0,1]
	v_pk_mul_f32 v[66:67], v[164:165], v[66:67] op_sel_hi:[0,1]
	v_cvt_pk_bf16_f32 v178, v68, v69
	v_cvt_pk_bf16_f32 v186, v64, v65
	v_cvt_pk_bf16_f32 v179, v70, v71
	v_cvt_pk_bf16_f32 v187, v66, v67
	v_add_u32_e32 v184, 0x6100, v132
	v_add_u32_e32 v185, 0x6120, v132
	global_store_dwordx2 v184, v[178:179], s[8:9]
	global_store_dwordx2 v185, v[186:187], s[8:9]
	v_pk_mul_f32 v[60:61], v[166:167], v[60:61] op_sel_hi:[0,1]
	v_pk_mul_f32 v[56:57], v[166:167], v[56:57] op_sel_hi:[0,1]
	v_pk_mul_f32 v[62:63], v[166:167], v[62:63] op_sel_hi:[0,1]
	v_pk_mul_f32 v[58:59], v[166:167], v[58:59] op_sel_hi:[0,1]
	v_cvt_pk_bf16_f32 v174, v60, v61
	v_cvt_pk_bf16_f32 v176, v56, v57
	v_cvt_pk_bf16_f32 v175, v62, v63
	v_cvt_pk_bf16_f32 v177, v58, v59
	v_add_u32_e32 v182, 0x10000, v132
	v_add_u32_e32 v183, 0x10020, v132
	global_store_dwordx2 v182, v[174:175], s[8:9]
	global_store_dwordx2 v183, v[176:177], s[8:9]
	v_pk_mul_f32 v[52:53], v[168:169], v[52:53] op_sel_hi:[0,1]
	v_pk_mul_f32 v[48:49], v[168:169], v[48:49] op_sel_hi:[0,1]
	v_pk_mul_f32 v[54:55], v[168:169], v[54:55] op_sel_hi:[0,1]
	v_pk_mul_f32 v[50:51], v[168:169], v[50:51] op_sel_hi:[0,1]
	v_cvt_pk_bf16_f32 v178, v52, v53
	v_cvt_pk_bf16_f32 v186, v48, v49
	v_cvt_pk_bf16_f32 v179, v54, v55
	v_cvt_pk_bf16_f32 v187, v50, v51
	v_add_u32_e32 v184, 0x12000, v132
	v_add_u32_e32 v185, 0x12020, v132
	global_store_dwordx2 v184, v[178:179], s[8:9]
	global_store_dwordx2 v185, v[186:187], s[8:9]
; template <int EPI>
; __device__ __forceinline__ void gemm_epi(const GemmArgs& G, const f32x4 (&a)[4][2], int rbase, int cbase, int fq, const float (&ssv)[4]) {
;   const int tn = cbase >> 8;
; #pragma unroll
;   for (int m = 0; m < 4; ++m) {
;     const int row = rbase + m * 16;
;     float rs = 1.f;
;     if constexpr (EPI == EPI_GU || EPI == EPI_EVIN || EPI == EPI_ODIN) rs = rsqrtf(ssv[m] * (1.f / 2048.f) + 1e-6f);
;     if constexpr (EPI == EPI_GU) {
;       const f32x4 gv = a[m][0] * rs, uv = a[m][1] * rs;
;       const int hc = (cbase >> 1) + fq * 4;
;       u32x2 o = {cvtpk(silu_f(gv[0]) * uv[0], silu_f(gv[1]) * uv[1]), cvtpk(silu_f(gv[2]) * uv[2], silu_f(gv[3]) * uv[3])};
;       *reinterpret_cast<u32x2*>(G.d0 + (size_t)(row - G.row0) * DFF + hc) = o;
;     } else {
; #pragma unroll
;       for (int n = 0; n < 2; ++n) {
;         const f32x4 v = a[m][n] * rs;
;         const int col = cbase + n * 16 + fq * 4;
;         if constexpr (EPI == EPI_POOL) {
;           const int cg_ = G.aux * 256 + col;
;           f32x4 sc = *reinterpret_cast<const f32x4*>(G.c0 + cg_);
;           u32x2 o = {cvtpk(v[0] * sc[0], v[1] * sc[1]), cvtpk(v[2] * sc[2], v[3] * sc[3])};
;           *reinterpret_cast<u32x2*>(G.d0 + (size_t)row * 1024 + cg_) = o;
;         } else if constexpr (EPI == EPI_EVIN) {
;           u32x2 o = {cvtpk(v[0], v[1]), cvtpk(v[2], v[3])};
;           u16* dp;
;           if (tn < 4) dp = G.d0 + (size_t)row * 1024 + col;
;           else if (tn < 8) dp = G.d1 + (size_t)row * 1024 + (col - 1024);
;           else if (tn == 8) dp = G.d2 + (size_t)row * 256 + (col - 2048);
;           else dp = G.d3 + (size_t)row * 256 + (col - 2304);
;           *reinterpret_cast<u32x2*>(dp) = o;
;         } else {
;           if (tn < 16) {
;             u32x2 o = {cvtpk(v[0], v[1]), cvtpk(v[2], v[3])};
;             u16* dp;
;             if (tn < 4) dp = G.d0 + (size_t)row * 1024 + col;
;             else if (tn == 4) dp = G.d1 + (size_t)row * 256 + (col - 1024);
;             else if (tn == 5) dp = G.d2 + (size_t)row * 256 + (col - 1280);
;             else if (tn < 10) dp = G.d3 + (size_t)row * 1024 + (col - 1536);
;             else dp = G.d4 + (size_t)row * 1536 + (col - 2560);
;             *reinterpret_cast<u32x2*>(dp) = o;
	v_pk_mul_f32 v[44:45], v[170:171], v[44:45] op_sel_hi:[0,1]
	v_pk_mul_f32 v[40:41], v[170:171], v[40:41] op_sel_hi:[0,1]
	v_pk_mul_f32 v[46:47], v[170:171], v[46:47] op_sel_hi:[0,1]
	v_pk_mul_f32 v[42:43], v[170:171], v[42:43] op_sel_hi:[0,1]
	v_cvt_pk_bf16_f32 v174, v44, v45
	v_cvt_pk_bf16_f32 v176, v40, v41
	v_cvt_pk_bf16_f32 v175, v46, v47
	v_cvt_pk_bf16_f32 v177, v42, v43
	v_add_u32_e32 v182, 0x14000, v132
	v_add_u32_e32 v183, 0x14020, v132
	global_store_dwordx2 v182, v[174:175], s[8:9]
	global_store_dwordx2 v183, v[176:177], s[8:9]
	v_pk_mul_f32 v[36:37], v[172:173], v[36:37] op_sel_hi:[0,1]
	v_pk_mul_f32 v[32:33], v[172:173], v[32:33] op_sel_hi:[0,1]
	v_pk_mul_f32 v[38:39], v[172:173], v[38:39] op_sel_hi:[0,1]
	v_pk_mul_f32 v[34:35], v[172:173], v[34:35] op_sel_hi:[0,1]
	v_cvt_pk_bf16_f32 v178, v36, v37
	v_cvt_pk_bf16_f32 v186, v32, v33
	v_cvt_pk_bf16_f32 v179, v38, v39
	v_cvt_pk_bf16_f32 v187, v34, v35
	v_add_u32_e32 v184, 0x16000, v132
	v_add_u32_e32 v185, 0x16020, v132
	global_store_dwordx2 v184, v[178:179], s[8:9]
	global_store_dwordx2 v185, v[186:187], s[8:9]
	v_pk_mul_f32 v[28:29], v[166:167], v[28:29] op_sel_hi:[0,1]
	v_pk_mul_f32 v[24:25], v[166:167], v[24:25] op_sel_hi:[0,1]
	v_pk_mul_f32 v[30:31], v[166:167], v[30:31] op_sel_hi:[0,1]
	v_pk_mul_f32 v[26:27], v[166:167], v[26:27] op_sel_hi:[0,1]
	v_cvt_pk_bf16_f32 v174, v28, v29
	v_cvt_pk_bf16_f32 v176, v24, v25
	v_cvt_pk_bf16_f32 v175, v30, v31
	v_cvt_pk_bf16_f32 v177, v26, v27
	v_add_u32_e32 v182, 0x10100, v132
	v_add_u32_e32 v183, 0x10120, v132
	global_store_dwordx2 v182, v[174:175], s[8:9]
	global_store_dwordx2 v183, v[176:177], s[8:9]
	v_pk_mul_f32 v[20:21], v[168:169], v[20:21] op_sel_hi:[0,1]
	v_pk_mul_f32 v[16:17], v[168:169], v[16:17] op_sel_hi:[0,1]
	v_pk_mul_f32 v[22:23], v[168:169], v[22:23] op_sel_hi:[0,1]
	v_pk_mul_f32 v[18:19], v[168:169], v[18:19] op_sel_hi:[0,1]
	v_cvt_pk_bf16_f32 v178, v20, v21
	v_cvt_pk_bf16_f32 v186, v16, v17
	v_cvt_pk_bf16_f32 v179, v22, v23
	v_cvt_pk_bf16_f32 v187, v18, v19
	v_add_u32_e32 v184, 0x12100, v132
	v_add_u32_e32 v185, 0x12120, v132
	global_store_dwordx2 v184, v[178:179], s[8:9]
	global_store_dwordx2 v185, v[186:187], s[8:9]
	v_pk_mul_f32 v[12:13], v[170:171], v[12:13] op_sel_hi:[0,1]
	v_pk_mul_f32 v[8:9], v[170:171], v[8:9] op_sel_hi:[0,1]
	v_pk_mul_f32 v[14:15], v[170:171], v[14:15] op_sel_hi:[0,1]
	v_pk_mul_f32 v[10:11], v[170:171], v[10:11] op_sel_hi:[0,1]
	v_cvt_pk_bf16_f32 v174, v12, v13
	v_cvt_pk_bf16_f32 v176, v8, v9
	v_cvt_pk_bf16_f32 v175, v14, v15
	v_cvt_pk_bf16_f32 v177, v10, v11
	v_add_u32_e32 v182, 0x14100, v132
	v_add_u32_e32 v183, 0x14120, v132
	global_store_dwordx2 v182, v[174:175], s[8:9]
	global_store_dwordx2 v183, v[176:177], s[8:9]
	v_pk_mul_f32 v[4:5], v[172:173], v[4:5] op_sel_hi:[0,1]
	v_pk_mul_f32 v[0:1], v[172:173], v[0:1] op_sel_hi:[0,1]
	v_pk_mul_f32 v[6:7], v[172:173], v[6:7] op_sel_hi:[0,1]
	v_pk_mul_f32 v[2:3], v[172:173], v[2:3] op_sel_hi:[0,1]
	v_cvt_pk_bf16_f32 v178, v4, v5
	v_cvt_pk_bf16_f32 v186, v0, v1
	v_cvt_pk_bf16_f32 v179, v6, v7
	v_cvt_pk_bf16_f32 v187, v2, v3
	v_add_u32_e32 v184, 0x16100, v132
	v_add_u32_e32 v185, 0x16120, v132
	global_store_dwordx2 v184, v[178:179], s[8:9]
	global_store_dwordx2 v185, v[186:187], s[8:9]
	s_branch .LBB0_738
.Lmy_od_p11:
	v_lshlrev_b32_e32 v132, 11, v129
	v_lshl_add_u32 v132, v131, 1, v132
	v_add_u32_e32 v132, s7, v132
	s_nop 1
	v_pk_mul_f32 v[124:125], v[158:159], v[124:125] op_sel_hi:[0,1]
	v_pk_mul_f32 v[120:121], v[158:159], v[120:121] op_sel_hi:[0,1]
	v_pk_mul_f32 v[126:127], v[158:159], v[126:127] op_sel_hi:[0,1]
	v_pk_mul_f32 v[122:123], v[158:159], v[122:123] op_sel_hi:[0,1]
	v_cvt_pk_bf16_f32 v174, v124, v125
	v_cvt_pk_bf16_f32 v176, v120, v121
	v_cvt_pk_bf16_f32 v175, v126, v127
	v_cvt_pk_bf16_f32 v177, v122, v123
	v_mov_b32_e32 v182, v132
	v_add_u32_e32 v183, 0x20, v132
	global_store_dwordx2 v182, v[174:175], s[8:9]
	global_store_dwordx2 v183, v[176:177], s[8:9]
	v_pk_mul_f32 v[116:117], v[160:161], v[116:117] op_sel_hi:[0,1]
	v_pk_mul_f32 v[112:113], v[160:161], v[112:113] op_sel_hi:[0,1]
	v_pk_mul_f32 v[118:119], v[160:161], v[118:119] op_sel_hi:[0,1]
	v_pk_mul_f32 v[114:115], v[160:161], v[114:115] op_sel_hi:[0,1]
	v_cvt_pk_bf16_f32 v178, v116, v117
	v_cvt_pk_bf16_f32 v186, v112, v113
	v_cvt_pk_bf16_f32 v179, v118, v119
	v_cvt_pk_bf16_f32 v187, v114, v115
	v_add_u32_e32 v184, 0x8000, v132
	v_add_u32_e32 v185, 0x8020, v132
	global_store_dwordx2 v184, v[178:179], s[8:9]
	global_store_dwordx2 v185, v[186:187], s[8:9]
	v_pk_mul_f32 v[108:109], v[162:163], v[108:109] op_sel_hi:[0,1]
	v_pk_mul_f32 v[104:105], v[162:163], v[104:105] op_sel_hi:[0,1]
	v_pk_mul_f32 v[110:111], v[162:163], v[110:111] op_sel_hi:[0,1]
	v_pk_mul_f32 v[106:107], v[162:163], v[106:107] op_sel_hi:[0,1]
	v_cvt_pk_bf16_f32 v174, v108, v109
	v_cvt_pk_bf16_f32 v176, v104, v105
	v_cvt_pk_bf16_f32 v175, v110, v111
	v_cvt_pk_bf16_f32 v177, v106, v107
	v_add_u32_e32 v182, 0x10000, v132
	v_add_u32_e32 v183, 0x10020, v132
	global_store_dwordx2 v182, v[174:175], s[8:9]
	global_store_dwordx2 v183, v[176:177], s[8:9]
	v_pk_mul_f32 v[100:101], v[164:165], v[100:101] op_sel_hi:[0,1]
	v_pk_mul_f32 v[96:97], v[164:165], v[96:97] op_sel_hi:[0,1]
	v_pk_mul_f32 v[102:103], v[164:165], v[102:103] op_sel_hi:[0,1]
	v_pk_mul_f32 v[98:99], v[164:165], v[98:99] op_sel_hi:[0,1]
	v_cvt_pk_bf16_f32 v178, v100, v101
	v_cvt_pk_bf16_f32 v186, v96, v97
	v_cvt_pk_bf16_f32 v179, v102, v103
	v_cvt_pk_bf16_f32 v187, v98, v99
	v_add_u32_e32 v184, 0x18000, v132
	v_add_u32_e32 v185, 0x18020, v132
	global_store_dwordx2 v184, v[178:179], s[8:9]
	global_store_dwordx2 v185, v[186:187], s[8:9]
; template <int EPI>
; __device__ __forceinline__ void gemm_epi(const GemmArgs& G, const f32x4 (&a)[4][2], int rbase, int cbase, int fq, const float (&ssv)[4]) {
;   const int tn = cbase >> 8;
; #pragma unroll
;   for (int m = 0; m < 4; ++m) {
;     const int row = rbase + m * 16;
;     float rs = 1.f;
;     if constexpr (EPI == EPI_GU || EPI == EPI_EVIN || EPI == EPI_ODIN) rs = rsqrtf(ssv[m] * (1.f / 2048.f) + 1e-6f);
;     if constexpr (EPI == EPI_GU) {
;       const f32x4 gv = a[m][0] * rs, uv = a[m][1] * rs;
;       const int hc = (cbase >> 1) + fq * 4;
;       u32x2 o = {cvtpk(silu_f(gv[0]) * uv[0], silu_f(gv[1]) * uv[1]), cvtpk(silu_f(gv[2]) * uv[2], silu_f(gv[3]) * uv[3])};
;       *reinterpret_cast<u32x2*>(G.d0 + (size_t)(row - G.row0) * DFF + hc) = o;
;     } else {
; #pragma unroll
;       for (int n = 0; n < 2; ++n) {
;         const f32x4 v = a[m][n] * rs;
;         const int col = cbase + n * 16 + fq * 4;
;         if constexpr (EPI == EPI_POOL) {
;           const int cg_ = G.aux * 256 + col;
;           f32x4 sc = *reinterpret_cast<const f32x4*>(G.c0 + cg_);
;           u32x2 o = {cvtpk(v[0] * sc[0], v[1] * sc[1]), cvtpk(v[2] * sc[2], v[3] * sc[3])};
;           *reinterpret_cast<u32x2*>(G.d0 + (size_t)row * 1024 + cg_) = o;
;         } else if constexpr (EPI == EPI_EVIN) {
;           u32x2 o = {cvtpk(v[0], v[1]), cvtpk(v[2], v[3])};
;           u16* dp;
;           if (tn < 4) dp = G.d0 + (size_t)row * 1024 + col;
;           else if (tn < 8) dp = G.d1 + (size_t)row * 1024 + (col - 1024);
;           else if (tn == 8) dp = G.d2 + (size_t)row * 256 + (col - 2048);
;           else dp = G.d3 + (size_t)row * 256 + (col - 2304);
;           *reinterpret_cast<u32x2*>(dp) = o;
;         } else {
;           if (tn < 16) {
;             u32x2 o = {cvtpk(v[0], v[1]), cvtpk(v[2], v[3])};
;             u16* dp;
;             if (tn < 4) dp = G.d0 + (size_t)row * 1024 + col;
;             else if (tn == 4) dp = G.d1 + (size_t)row * 256 + (col - 1024);
;             else if (tn == 5) dp = G.d2 + (size_t)row * 256 + (col - 1280);
;             else if (tn < 10) dp = G.d3 + (size_t)row * 1024 + (col - 1536);
;             else dp = G.d4 + (size_t)row * 1536 + (col - 2560);
;             *reinterpret_cast<u32x2*>(dp) = o;
	v_pk_mul_f32 v[92:93], v[158:159], v[92:93] op_sel_hi:[0,1]
	v_pk_mul_f32 v[88:89], v[158:159], v[88:89] op_sel_hi:[0,1]
	v_pk_mul_f32 v[94:95], v[158:159], v[94:95] op_sel_hi:[0,1]
	v_pk_mul_f32 v[90:91], v[158:159], v[90:91] op_sel_hi:[0,1]
	v_cvt_pk_bf16_f32 v174, v92, v93
	v_cvt_pk_bf16_f32 v176, v88, v89
	v_cvt_pk_bf16_f32 v175, v94, v95
	v_cvt_pk_bf16_f32 v177, v90, v91
	v_add_u32_e32 v182, 0x100, v132
	v_add_u32_e32 v183, 0x120, v132
	global_store_dwordx2 v182, v[174:175], s[8:9]
	global_store_dwordx2 v183, v[176:177], s[8:9]
	v_pk_mul_f32 v[84:85], v[160:161], v[84:85] op_sel_hi:[0,1]
	v_pk_mul_f32 v[80:81], v[160:161], v[80:81] op_sel_hi:[0,1]
	v_pk_mul_f32 v[86:87], v[160:161], v[86:87] op_sel_hi:[0,1]
	v_pk_mul_f32 v[82:83], v[160:161], v[82:83] op_sel_hi:[0,1]
	v_cvt_pk_bf16_f32 v178, v84, v85
	v_cvt_pk_bf16_f32 v186, v80, v81
	v_cvt_pk_bf16_f32 v179, v86, v87
	v_cvt_pk_bf16_f32 v187, v82, v83
	v_add_u32_e32 v184, 0x8100, v132
	v_add_u32_e32 v185, 0x8120, v132
	global_store_dwordx2 v184, v[178:179], s[8:9]
	global_store_dwordx2 v185, v[186:187], s[8:9]
	v_pk_mul_f32 v[76:77], v[162:163], v[76:77] op_sel_hi:[0,1]
	v_pk_mul_f32 v[72:73], v[162:163], v[72:73] op_sel_hi:[0,1]
	v_pk_mul_f32 v[78:79], v[162:163], v[78:79] op_sel_hi:[0,1]
	v_pk_mul_f32 v[74:75], v[162:163], v[74:75] op_sel_hi:[0,1]
	v_cvt_pk_bf16_f32 v174, v76, v77
	v_cvt_pk_bf16_f32 v176, v72, v73
	v_cvt_pk_bf16_f32 v175, v78, v79
	v_cvt_pk_bf16_f32 v177, v74, v75
	v_add_u32_e32 v182, 0x10100, v132
	v_add_u32_e32 v183, 0x10120, v132
	global_store_dwordx2 v182, v[174:175], s[8:9]
	global_store_dwordx2 v183, v[176:177], s[8:9]
	v_pk_mul_f32 v[68:69], v[164:165], v[68:69] op_sel_hi:[0,1]
	v_pk_mul_f32 v[64:65], v[164:165], v[64:65] op_sel_hi:[0,1]
	v_pk_mul_f32 v[70:71], v[164:165], v[70:71] op_sel_hi:[0,1]
	v_pk_mul_f32 v[66:67], v[164:165], v[66:67] op_sel_hi:[0,1]
	v_cvt_pk_bf16_f32 v178, v68, v69
	v_cvt_pk_bf16_f32 v186, v64, v65
	v_cvt_pk_bf16_f32 v179, v70, v71
	v_cvt_pk_bf16_f32 v187, v66, v67
	v_add_u32_e32 v184, 0x18100, v132
	v_add_u32_e32 v185, 0x18120, v132
	global_store_dwordx2 v184, v[178:179], s[8:9]
	global_store_dwordx2 v185, v[186:187], s[8:9]
	v_pk_mul_f32 v[60:61], v[166:167], v[60:61] op_sel_hi:[0,1]
	v_pk_mul_f32 v[56:57], v[166:167], v[56:57] op_sel_hi:[0,1]
	v_pk_mul_f32 v[62:63], v[166:167], v[62:63] op_sel_hi:[0,1]
	v_pk_mul_f32 v[58:59], v[166:167], v[58:59] op_sel_hi:[0,1]
	v_cvt_pk_bf16_f32 v174, v60, v61
	v_cvt_pk_bf16_f32 v176, v56, v57
	v_cvt_pk_bf16_f32 v175, v62, v63
	v_cvt_pk_bf16_f32 v177, v58, v59
	v_add_u32_e32 v182, 0x40000, v132
	v_add_u32_e32 v183, 0x40020, v132
	global_store_dwordx2 v182, v[174:175], s[8:9]
	global_store_dwordx2 v183, v[176:177], s[8:9]
	v_pk_mul_f32 v[52:53], v[168:169], v[52:53] op_sel_hi:[0,1]
	v_pk_mul_f32 v[48:49], v[168:169], v[48:49] op_sel_hi:[0,1]
	v_pk_mul_f32 v[54:55], v[168:169], v[54:55] op_sel_hi:[0,1]
	v_pk_mul_f32 v[50:51], v[168:169], v[50:51] op_sel_hi:[0,1]
	v_cvt_pk_bf16_f32 v178, v52, v53
	v_cvt_pk_bf16_f32 v186, v48, v49
	v_cvt_pk_bf16_f32 v179, v54, v55
	v_cvt_pk_bf16_f32 v187, v50, v51
	v_add_u32_e32 v184, 0x48000, v132
	v_add_u32_e32 v185, 0x48020, v132
	global_store_dwordx2 v184, v[178:179], s[8:9]
	global_store_dwordx2 v185, v[186:187], s[8:9]
	v_pk_mul_f32 v[44:45], v[170:171], v[44:45] op_sel_hi:[0,1]
	v_pk_mul_f32 v[40:41], v[170:171], v[40:41] op_sel_hi:[0,1]
	v_pk_mul_f32 v[46:47], v[170:171], v[46:47] op_sel_hi:[0,1]
	v_pk_mul_f32 v[42:43], v[170:171], v[42:43] op_sel_hi:[0,1]
	v_cvt_pk_bf16_f32 v174, v44, v45
	v_cvt_pk_bf16_f32 v176, v40, v41
	v_cvt_pk_bf16_f32 v175, v46, v47
	v_cvt_pk_bf16_f32 v177, v42, v43
	v_add_u32_e32 v182, 0x50000, v132
	v_add_u32_e32 v183, 0x50020, v132
	global_store_dwordx2 v182, v[174:175], s[8:9]
	global_store_dwordx2 v183, v[176:177], s[8:9]
	v_pk_mul_f32 v[36:37], v[172:173], v[36:37] op_sel_hi:[0,1]
	v_pk_mul_f32 v[32:33], v[172:173], v[32:33] op_sel_hi:[0,1]
	v_pk_mul_f32 v[38:39], v[172:173], v[38:39] op_sel_hi:[0,1]
	v_pk_mul_f32 v[34:35], v[172:173], v[34:35] op_sel_hi:[0,1]
	v_cvt_pk_bf16_f32 v178, v36, v37
	v_cvt_pk_bf16_f32 v186, v32, v33
	v_cvt_pk_bf16_f32 v179, v38, v39
	v_cvt_pk_bf16_f32 v187, v34, v35
	v_add_u32_e32 v184, 0x58000, v132
	v_add_u32_e32 v185, 0x58020, v132
	global_store_dwordx2 v184, v[178:179], s[8:9]
	global_store_dwordx2 v185, v[186:187], s[8:9]
	v_pk_mul_f32 v[28:29], v[166:167], v[28:29] op_sel_hi:[0,1]
	v_pk_mul_f32 v[24:25], v[166:167], v[24:25] op_sel_hi:[0,1]
	v_pk_mul_f32 v[30:31], v[166:167], v[30:31] op_sel_hi:[0,1]
	v_pk_mul_f32 v[26:27], v[166:167], v[26:27] op_sel_hi:[0,1]
	v_cvt_pk_bf16_f32 v174, v28, v29
	v_cvt_pk_bf16_f32 v176, v24, v25
	v_cvt_pk_bf16_f32 v175, v30, v31
	v_cvt_pk_bf16_f32 v177, v26, v27
	v_add_u32_e32 v182, 0x40100, v132
	v_add_u32_e32 v183, 0x40120, v132
	global_store_dwordx2 v182, v[174:175], s[8:9]
	global_store_dwordx2 v183, v[176:177], s[8:9]
	v_pk_mul_f32 v[20:21], v[168:169], v[20:21] op_sel_hi:[0,1]
	v_pk_mul_f32 v[16:17], v[168:169], v[16:17] op_sel_hi:[0,1]
	v_pk_mul_f32 v[22:23], v[168:169], v[22:23] op_sel_hi:[0,1]
	v_pk_mul_f32 v[18:19], v[168:169], v[18:19] op_sel_hi:[0,1]
	v_cvt_pk_bf16_f32 v178, v20, v21
	v_cvt_pk_bf16_f32 v186, v16, v17
	v_cvt_pk_bf16_f32 v179, v22, v23
	v_cvt_pk_bf16_f32 v187, v18, v19
	v_add_u32_e32 v184, 0x48100, v132
	v_add_u32_e32 v185, 0x48120, v132
	global_store_dwordx2 v184, v[178:179], s[8:9]
	global_store_dwordx2 v185, v[186:187], s[8:9]
	v_pk_mul_f32 v[12:13], v[170:171], v[12:13] op_sel_hi:[0,1]
	v_pk_mul_f32 v[8:9], v[170:171], v[8:9] op_sel_hi:[0,1]
	v_pk_mul_f32 v[14:15], v[170:171], v[14:15] op_sel_hi:[0,1]
	v_pk_mul_f32 v[10:11], v[170:171], v[10:11] op_sel_hi:[0,1]
	v_cvt_pk_bf16_f32 v174, v12, v13
	v_cvt_pk_bf16_f32 v176, v8, v9
	v_cvt_pk_bf16_f32 v175, v14, v15
	v_cvt_pk_bf16_f32 v177, v10, v11
	v_add_u32_e32 v182, 0x50100, v132
	v_add_u32_e32 v183, 0x50120, v132
	global_store_dwordx2 v182, v[174:175], s[8:9]
	global_store_dwordx2 v183, v[176:177], s[8:9]
	v_pk_mul_f32 v[4:5], v[172:173], v[4:5] op_sel_hi:[0,1]
	v_pk_mul_f32 v[0:1], v[172:173], v[0:1] op_sel_hi:[0,1]
	v_pk_mul_f32 v[6:7], v[172:173], v[6:7] op_sel_hi:[0,1]
	v_pk_mul_f32 v[2:3], v[172:173], v[2:3] op_sel_hi:[0,1]
	v_cvt_pk_bf16_f32 v178, v4, v5
	v_cvt_pk_bf16_f32 v186, v0, v1
	v_cvt_pk_bf16_f32 v179, v6, v7
	v_cvt_pk_bf16_f32 v187, v2, v3
	v_add_u32_e32 v184, 0x58100, v132
	v_add_u32_e32 v185, 0x58120, v132
	global_store_dwordx2 v184, v[178:179], s[8:9]
	global_store_dwordx2 v185, v[186:187], s[8:9]
	s_branch .LBB0_738

; template <int EPI>
; __device__ __forceinline__ void gemm_phase(const GemmArgs& G, char* shm) {
;     ...
;   for (int t = vb; t < nwg; t += gridDim.x) {
;     int brow, bcol, nbrow = 0, nbcol = 0; gemm_map_tile(G, t, brow, bcol);
;     const bool has_next = t + (int)gridDim.x < nwg;
;     if (has_next) gemm_map_tile(G, t + gridDim.x, nbrow, nbcol);
;     gemm_tile<EPI>(G, brow, bcol, shm, t == vb, has_next, nbrow, nbcol);
;   }
.LBB0_1856:
.Lmy_ev_done:
	s_andn2_b64 vcc, exec, s[22:23]
	s_mov_b32 s24, s41
	s_cbranch_vccz .LBB0_2254

; __device__ __forceinline__ float silu_f(float x) { return x * __builtin_amdgcn_rcpf(1.f + __builtin_amdgcn_exp2f(-1.4426950408889634f * x)); }
; template <int EPI>
; __device__ __forceinline__ void gemm_epi(const GemmArgs& G, const f32x4 (&a)[4][2], int rbase, int cbase, int fq, const float (&ssv)[4]) {
;   const int tn = cbase >> 8;
; #pragma unroll
;   for (int m = 0; m < 4; ++m) {
;     const int row = rbase + m * 16;
;     float rs = 1.f;
;     if constexpr (EPI == EPI_GU || EPI == EPI_EVIN || EPI == EPI_ODIN) rs = rsqrtf(ssv[m] * (1.f / 2048.f) + 1e-6f);
;     if constexpr (EPI == EPI_GU) {
;       const f32x4 gv = a[m][0] * rs, uv = a[m][1] * rs;
;       const int hc = (cbase >> 1) + fq * 4;
;       u32x2 o = {cvtpk(silu_f(gv[0]) * uv[0], silu_f(gv[1]) * uv[1]), cvtpk(silu_f(gv[2]) * uv[2], silu_f(gv[3]) * uv[3])};
;       *reinterpret_cast<u32x2*>(G.d0 + (size_t)(row - G.row0) * DFF + hc) = o;
;     } else {
; #pragma unroll
;       for (int n = 0; n < 2; ++n) {
;         const f32x4 v = a[m][n] * rs;
;         const int col = cbase + n * 16 + fq * 4;
;         if constexpr (EPI == EPI_POOL) {
;           const int cg_ = G.aux * 256 + col;
;           f32x4 sc = *reinterpret_cast<const f32x4*>(G.c0 + cg_);
;           u32x2 o = {cvtpk(v[0] * sc[0], v[1] * sc[1]), cvtpk(v[2] * sc[2], v[3] * sc[3])};
;           *reinterpret_cast<u32x2*>(G.d0 + (size_t)row * 1024 + cg_) = o;
;         } else if constexpr (EPI == EPI_EVIN) {
;           u32x2 o = {cvtpk(v[0], v[1]), cvtpk(v[2], v[3])};
;           u16* dp;
;           if (tn < 4) dp = G.d0 + (size_t)row * 1024 + col;
;           else if (tn < 8) dp = G.d1 + (size_t)row * 1024 + (col - 1024);
;           else if (tn == 8) dp = G.d2 + (size_t)row * 256 + (col - 2048);
;           else dp = G.d3 + (size_t)row * 256 + (col - 2304);
;           *reinterpret_cast<u32x2*>(dp) = o;
.LBB0_1870:
	v_readfirstlane_b32 s6, v224
	s_andn2_b32 s6, s6, 63
	s_nop 0
	v_add_u32_e32 v128, s6, v225
	v_and_b32_e32 v129, 15, v128
	v_ashrrev_i32_e32 v131, 2, v128
	v_and_or_b32 v129, v131, 64, v129
	v_lshrrev_b32_e32 v131, 1, v128
	v_and_b32_e32 v131, 0x60, v131
	v_lshrrev_b32_e32 v128, 2, v128
	v_and_or_b32 v131, v128, 12, v131
	v_add_u32_e32 v129, s29, v129
	v_add_u32_e32 v131, s24, v131
	v_mov_b32_e32 v249, v226
	s_waitcnt vmcnt(8)
	v_fmamk_f32 v154, v130, 0x3a000000, v229
	v_fmamk_f32 v156, v152, 0x3a000000, v229
	v_fmamk_f32 v158, v151, 0x3a000000, v229
	v_fmamk_f32 v160, v150, 0x3a000000, v229
	v_fmamk_f32 v162, v145, 0x3a000000, v229
	v_fmamk_f32 v164, v144, 0x3a000000, v229
	v_fmamk_f32 v166, v143, 0x3a000000, v229
	v_fmamk_f32 v168, v142, 0x3a000000, v229
	v_rsq_f32_e32 v154, v154
	v_rsq_f32_e32 v156, v156
	v_rsq_f32_e32 v158, v158
	v_rsq_f32_e32 v160, v160
	v_rsq_f32_e32 v162, v162
	v_rsq_f32_e32 v164, v164
	v_rsq_f32_e32 v166, v166
	v_rsq_f32_e32 v168, v168
	s_lshr_b32 s6, s24, 8
	s_mov_b64 s[8:9], s[18:19]
	s_mov_b32 s7, 0
	s_cmp_lt_u32 s6, 4
	s_cbranch_scc1 .Lmy_ev_p11
	s_mov_b64 s[8:9], s[12:13]
	s_movk_i32 s7, 0xf800
	s_cmp_lt_u32 s6, 8
	s_cbranch_scc1 .Lmy_ev_p11
	s_mov_b64 s[8:9], s[14:15]
	s_movk_i32 s7, 0xf000
	s_cmp_eq_u32 s6, 8
	s_cbranch_scc1 .Lmy_ev_p9
	s_mov_b64 s[8:9], s[16:17]
	s_movk_i32 s7, 0xee00
.Lmy_ev_p9:
	v_lshlrev_b32_e32 v132, 9, v129
	v_lshl_add_u32 v132, v131, 1, v132
	v_add_u32_e32 v132, s7, v132
	v_pk_mul_f32 v[124:125], v[154:155], v[124:125] op_sel_hi:[0,1]
	v_pk_mul_f32 v[120:121], v[154:155], v[120:121] op_sel_hi:[0,1]
	v_pk_mul_f32 v[126:127], v[154:155], v[126:127] op_sel_hi:[0,1]
	v_pk_mul_f32 v[122:123], v[154:155], v[122:123] op_sel_hi:[0,1]
	v_cvt_pk_bf16_f32 v170, v124, v125
	v_cvt_pk_bf16_f32 v172, v120, v121
	v_cvt_pk_bf16_f32 v171, v126, v127
	v_cvt_pk_bf16_f32 v173, v122, v123
	v_mov_b32_e32 v178, v132
	v_add_u32_e32 v179, 0x20, v132
	global_store_dwordx2 v178, v[170:171], s[8:9]
	global_store_dwordx2 v179, v[172:173], s[8:9]
	v_pk_mul_f32 v[116:117], v[156:157], v[116:117] op_sel_hi:[0,1]
	v_pk_mul_f32 v[112:113], v[156:157], v[112:113] op_sel_hi:[0,1]
	v_pk_mul_f32 v[118:119], v[156:157], v[118:119] op_sel_hi:[0,1]
	v_pk_mul_f32 v[114:115], v[156:157], v[114:115] op_sel_hi:[0,1]
	v_cvt_pk_bf16_f32 v174, v116, v117
	v_cvt_pk_bf16_f32 v176, v112, v113
	v_cvt_pk_bf16_f32 v175, v118, v119
	v_cvt_pk_bf16_f32 v177, v114, v115
	v_add_u32_e32 v182, 0x2000, v132
	v_add_u32_e32 v183, 0x2020, v132
	global_store_dwordx2 v182, v[174:175], s[8:9]
	global_store_dwordx2 v183, v[176:177], s[8:9]
	v_pk_mul_f32 v[108:109], v[158:159], v[108:109] op_sel_hi:[0,1]
	v_pk_mul_f32 v[104:105], v[158:159], v[104:105] op_sel_hi:[0,1]
	v_pk_mul_f32 v[110:111], v[158:159], v[110:111] op_sel_hi:[0,1]
	v_pk_mul_f32 v[106:107], v[158:159], v[106:107] op_sel_hi:[0,1]
	v_cvt_pk_bf16_f32 v170, v108, v109
	v_cvt_pk_bf16_f32 v172, v104, v105
	v_cvt_pk_bf16_f32 v171, v110, v111
	v_cvt_pk_bf16_f32 v173, v106, v107
	v_add_u32_e32 v178, 0x4000, v132
	v_add_u32_e32 v179, 0x4020, v132
	global_store_dwordx2 v178, v[170:171], s[8:9]
	global_store_dwordx2 v179, v[172:173], s[8:9]
	v_pk_mul_f32 v[100:101], v[160:161], v[100:101] op_sel_hi:[0,1]
	v_pk_mul_f32 v[96:97], v[160:161], v[96:97] op_sel_hi:[0,1]
	v_pk_mul_f32 v[102:103], v[160:161], v[102:103] op_sel_hi:[0,1]
	v_pk_mul_f32 v[98:99], v[160:161], v[98:99] op_sel_hi:[0,1]
	v_cvt_pk_bf16_f32 v174, v100, v101
	v_cvt_pk_bf16_f32 v176, v96, v97
	v_cvt_pk_bf16_f32 v175, v102, v103
	v_cvt_pk_bf16_f32 v177, v98, v99
	v_add_u32_e32 v182, 0x6000, v132
	v_add_u32_e32 v183, 0x6020, v132
	global_store_dwordx2 v182, v[174:175], s[8:9]
	global_store_dwordx2 v183, v[176:177], s[8:9]
	v_pk_mul_f32 v[92:93], v[154:155], v[92:93] op_sel_hi:[0,1]
	v_pk_mul_f32 v[88:89], v[154:155], v[88:89] op_sel_hi:[0,1]
	v_pk_mul_f32 v[94:95], v[154:155], v[94:95] op_sel_hi:[0,1]
	v_pk_mul_f32 v[90:91], v[154:155], v[90:91] op_sel_hi:[0,1]
	v_cvt_pk_bf16_f32 v170, v92, v93
	v_cvt_pk_bf16_f32 v172, v88, v89
	v_cvt_pk_bf16_f32 v171, v94, v95
	v_cvt_pk_bf16_f32 v173, v90, v91
	v_add_u32_e32 v178, 0x100, v132
	v_add_u32_e32 v179, 0x120, v132
	global_store_dwordx2 v178, v[170:171], s[8:9]
	global_store_dwordx2 v179, v[172:173], s[8:9]
	v_pk_mul_f32 v[84:85], v[156:157], v[84:85] op_sel_hi:[0,1]
	v_pk_mul_f32 v[80:81], v[156:157], v[80:81] op_sel_hi:[0,1]
	v_pk_mul_f32 v[86:87], v[156:157], v[86:87] op_sel_hi:[0,1]
	v_pk_mul_f32 v[82:83], v[156:157], v[82:83] op_sel_hi:[0,1]
	v_cvt_pk_bf16_f32 v174, v84, v85
	v_cvt_pk_bf16_f32 v176, v80, v81
	v_cvt_pk_bf16_f32 v175, v86, v87
	v_cvt_pk_bf16_f32 v177, v82, v83
	v_add_u32_e32 v182, 0x2100, v132
	v_add_u32_e32 v183, 0x2120, v132
	global_store_dwordx2 v182, v[174:175], s[8:9]
	global_store_dwordx2 v183, v[176:177], s[8:9]
	v_pk_mul_f32 v[76:77], v[158:159], v[76:77] op_sel_hi:[0,1]
	v_pk_mul_f32 v[72:73], v[158:159], v[72:73] op_sel_hi:[0,1]
	v_pk_mul_f32 v[78:79], v[158:159], v[78:79] op_sel_hi:[0,1]
	v_pk_mul_f32 v[74:75], v[158:159], v[74:75] op_sel_hi:[0,1]
	v_cvt_pk_bf16_f32 v170, v76, v77
	v_cvt_pk_bf16_f32 v172, v72, v73
	v_cvt_pk_bf16_f32 v171, v78, v79
	v_cvt_pk_bf16_f32 v173, v74, v75
	v_add_u32_e32 v178, 0x4100, v132
	v_add_u32_e32 v179, 0x4120, v132
	global_store_dwordx2 v178, v[170:171], s[8:9]
	global_store_dwordx2 v179, v[172:173], s[8:9]
	v_pk_mul_f32 v[68:69], v[160:161], v[68:69] op_sel_hi:[0,1]
	v_pk_mul_f32 v[64:65], v[160:161], v[64:65] op_sel_hi:[0,1]
	v_pk_mul_f32 v[70:71], v[160:161], v[70:71] op_sel_hi:[0,1]
	v_pk_mul_f32 v[66:67], v[160:161], v[66:67] op_sel_hi:[0,1]
	v_cvt_pk_bf16_f32 v174, v68, v69
	v_cvt_pk_bf16_f32 v176, v64, v65
; __device__ __forceinline__ float silu_f(float x) { return x * __builtin_amdgcn_rcpf(1.f + __builtin_amdgcn_exp2f(-1.4426950408889634f * x)); }
; template <int EPI>
; __device__ __forceinline__ void gemm_epi(const GemmArgs& G, const f32x4 (&a)[4][2], int rbase, int cbase, int fq, const float (&ssv)[4]) {
;   const int tn = cbase >> 8;
; #pragma unroll
;   for (int m = 0; m < 4; ++m) {
;     const int row = rbase + m * 16;
;     float rs = 1.f;
;     if constexpr (EPI == EPI_GU || EPI == EPI_EVIN || EPI == EPI_ODIN) rs = rsqrtf(ssv[m] * (1.f / 2048.f) + 1e-6f);
;     if constexpr (EPI == EPI_GU) {
;       const f32x4 gv = a[m][0] * rs, uv = a[m][1] * rs;
;       const int hc = (cbase >> 1) + fq * 4;
;       u32x2 o = {cvtpk(silu_f(gv[0]) * uv[0], silu_f(gv[1]) * uv[1]), cvtpk(silu_f(gv[2]) * uv[2], silu_f(gv[3]) * uv[3])};
;       *reinterpret_cast<u32x2*>(G.d0 + (size_t)(row - G.row0) * DFF + hc) = o;
;     } else {
; #pragma unroll
;       for (int n = 0; n < 2; ++n) {
;         const f32x4 v = a[m][n] * rs;
;         const int col = cbase + n * 16 + fq * 4;
;         if constexpr (EPI == EPI_POOL) {
;           const int cg_ = G.aux * 256 + col;
;           f32x4 sc = *reinterpret_cast<const f32x4*>(G.c0 + cg_);
;           u32x2 o = {cvtpk(v[0] * sc[0], v[1] * sc[1]), cvtpk(v[2] * sc[2], v[3] * sc[3])};
;           *reinterpret_cast<u32x2*>(G.d0 + (size_t)row * 1024 + cg_) = o;
;         } else if constexpr (EPI == EPI_EVIN) {
;           u32x2 o = {cvtpk(v[0], v[1]), cvtpk(v[2], v[3])};
;           u16* dp;
;           if (tn < 4) dp = G.d0 + (size_t)row * 1024 + col;
;           else if (tn < 8) dp = G.d1 + (size_t)row * 1024 + (col - 1024);
;           else if (tn == 8) dp = G.d2 + (size_t)row * 256 + (col - 2048);
;           else dp = G.d3 + (size_t)row * 256 + (col - 2304);
;           *reinterpret_cast<u32x2*>(dp) = o;
	v_cvt_pk_bf16_f32 v175, v70, v71
	v_cvt_pk_bf16_f32 v177, v66, v67
	v_add_u32_e32 v182, 0x6100, v132
	v_add_u32_e32 v183, 0x6120, v132
	global_store_dwordx2 v182, v[174:175], s[8:9]
	global_store_dwordx2 v183, v[176:177], s[8:9]
	v_pk_mul_f32 v[60:61], v[162:163], v[60:61] op_sel_hi:[0,1]
	v_pk_mul_f32 v[56:57], v[162:163], v[56:57] op_sel_hi:[0,1]
	v_pk_mul_f32 v[62:63], v[162:163], v[62:63] op_sel_hi:[0,1]
	v_pk_mul_f32 v[58:59], v[162:163], v[58:59] op_sel_hi:[0,1]
	v_cvt_pk_bf16_f32 v170, v60, v61
	v_cvt_pk_bf16_f32 v172, v56, v57
	v_cvt_pk_bf16_f32 v171, v62, v63
	v_cvt_pk_bf16_f32 v173, v58, v59
	v_add_u32_e32 v178, 0x10000, v132
	v_add_u32_e32 v179, 0x10020, v132
	global_store_dwordx2 v178, v[170:171], s[8:9]
	global_store_dwordx2 v179, v[172:173], s[8:9]
	v_pk_mul_f32 v[52:53], v[164:165], v[52:53] op_sel_hi:[0,1]
	v_pk_mul_f32 v[48:49], v[164:165], v[48:49] op_sel_hi:[0,1]
	v_pk_mul_f32 v[54:55], v[164:165], v[54:55] op_sel_hi:[0,1]
	v_pk_mul_f32 v[50:51], v[164:165], v[50:51] op_sel_hi:[0,1]
	v_cvt_pk_bf16_f32 v174, v52, v53
	v_cvt_pk_bf16_f32 v176, v48, v49
	v_cvt_pk_bf16_f32 v175, v54, v55
	v_cvt_pk_bf16_f32 v177, v50, v51
	v_add_u32_e32 v182, 0x12000, v132
	v_add_u32_e32 v183, 0x12020, v132
	global_store_dwordx2 v182, v[174:175], s[8:9]
	global_store_dwordx2 v183, v[176:177], s[8:9]
	v_pk_mul_f32 v[44:45], v[166:167], v[44:45] op_sel_hi:[0,1]
	v_pk_mul_f32 v[40:41], v[166:167], v[40:41] op_sel_hi:[0,1]
	v_pk_mul_f32 v[46:47], v[166:167], v[46:47] op_sel_hi:[0,1]
	v_pk_mul_f32 v[42:43], v[166:167], v[42:43] op_sel_hi:[0,1]
	v_cvt_pk_bf16_f32 v170, v44, v45
	v_cvt_pk_bf16_f32 v172, v40, v41
	v_cvt_pk_bf16_f32 v171, v46, v47
	v_cvt_pk_bf16_f32 v173, v42, v43
	v_add_u32_e32 v178, 0x14000, v132
	v_add_u32_e32 v179, 0x14020, v132
	global_store_dwordx2 v178, v[170:171], s[8:9]
	global_store_dwordx2 v179, v[172:173], s[8:9]
	v_pk_mul_f32 v[36:37], v[168:169], v[36:37] op_sel_hi:[0,1]
	v_pk_mul_f32 v[32:33], v[168:169], v[32:33] op_sel_hi:[0,1]
	v_pk_mul_f32 v[38:39], v[168:169], v[38:39] op_sel_hi:[0,1]
	v_pk_mul_f32 v[34:35], v[168:169], v[34:35] op_sel_hi:[0,1]
	v_cvt_pk_bf16_f32 v174, v36, v37
	v_cvt_pk_bf16_f32 v176, v32, v33
	v_cvt_pk_bf16_f32 v175, v38, v39
	v_cvt_pk_bf16_f32 v177, v34, v35
	v_add_u32_e32 v182, 0x16000, v132
	v_add_u32_e32 v183, 0x16020, v132
	global_store_dwordx2 v182, v[174:175], s[8:9]
	global_store_dwordx2 v183, v[176:177], s[8:9]
	v_pk_mul_f32 v[28:29], v[162:163], v[28:29] op_sel_hi:[0,1]
	v_pk_mul_f32 v[24:25], v[162:163], v[24:25] op_sel_hi:[0,1]
	v_pk_mul_f32 v[30:31], v[162:163], v[30:31] op_sel_hi:[0,1]
	v_pk_mul_f32 v[26:27], v[162:163], v[26:27] op_sel_hi:[0,1]
	v_cvt_pk_bf16_f32 v170, v28, v29
	v_cvt_pk_bf16_f32 v172, v24, v25
	v_cvt_pk_bf16_f32 v171, v30, v31
	v_cvt_pk_bf16_f32 v173, v26, v27
	v_add_u32_e32 v178, 0x10100, v132
	v_add_u32_e32 v179, 0x10120, v132
	global_store_dwordx2 v178, v[170:171], s[8:9]
	global_store_dwordx2 v179, v[172:173], s[8:9]
	v_pk_mul_f32 v[20:21], v[164:165], v[20:21] op_sel_hi:[0,1]
	v_pk_mul_f32 v[16:17], v[164:165], v[16:17] op_sel_hi:[0,1]
	v_pk_mul_f32 v[22:23], v[164:165], v[22:23] op_sel_hi:[0,1]
	v_pk_mul_f32 v[18:19], v[164:165], v[18:19] op_sel_hi:[0,1]
	v_cvt_pk_bf16_f32 v174, v20, v21
	v_cvt_pk_bf16_f32 v176, v16, v17
	v_cvt_pk_bf16_f32 v175, v22, v23
	v_cvt_pk_bf16_f32 v177, v18, v19
	v_add_u32_e32 v182, 0x12100, v132
	v_add_u32_e32 v183, 0x12120, v132
	global_store_dwordx2 v182, v[174:175], s[8:9]
	global_store_dwordx2 v183, v[176:177], s[8:9]
	v_pk_mul_f32 v[12:13], v[166:167], v[12:13] op_sel_hi:[0,1]
	v_pk_mul_f32 v[8:9], v[166:167], v[8:9] op_sel_hi:[0,1]
	v_pk_mul_f32 v[14:15], v[166:167], v[14:15] op_sel_hi:[0,1]
	v_pk_mul_f32 v[10:11], v[166:167], v[10:11] op_sel_hi:[0,1]
	v_cvt_pk_bf16_f32 v170, v12, v13
	v_cvt_pk_bf16_f32 v172, v8, v9
	v_cvt_pk_bf16_f32 v171, v14, v15
	v_cvt_pk_bf16_f32 v173, v10, v11
	v_add_u32_e32 v178, 0x14100, v132
	v_add_u32_e32 v179, 0x14120, v132
	global_store_dwordx2 v178, v[170:171], s[8:9]
	global_store_dwordx2 v179, v[172:173], s[8:9]
	v_pk_mul_f32 v[4:5], v[168:169], v[4:5] op_sel_hi:[0,1]
	v_pk_mul_f32 v[0:1], v[168:169], v[0:1] op_sel_hi:[0,1]
	v_pk_mul_f32 v[6:7], v[168:169], v[6:7] op_sel_hi:[0,1]
	v_pk_mul_f32 v[2:3], v[168:169], v[2:3] op_sel_hi:[0,1]
	v_cvt_pk_bf16_f32 v174, v4, v5
	v_cvt_pk_bf16_f32 v176, v0, v1
	v_cvt_pk_bf16_f32 v175, v6, v7
	v_cvt_pk_bf16_f32 v177, v2, v3
	v_add_u32_e32 v182, 0x16100, v132
	v_add_u32_e32 v183, 0x16120, v132
	global_store_dwordx2 v182, v[174:175], s[8:9]
	global_store_dwordx2 v183, v[176:177], s[8:9]
	s_branch .Lmy_ev_done
; __device__ __forceinline__ float silu_f(float x) { return x * __builtin_amdgcn_rcpf(1.f + __builtin_amdgcn_exp2f(-1.4426950408889634f * x)); }
; template <int EPI>
; __device__ __forceinline__ void gemm_epi(const GemmArgs& G, const f32x4 (&a)[4][2], int rbase, int cbase, int fq, const float (&ssv)[4]) {
;   const int tn = cbase >> 8;
; #pragma unroll
;   for (int m = 0; m < 4; ++m) {
;     const int row = rbase + m * 16;
;     float rs = 1.f;
;     if constexpr (EPI == EPI_GU || EPI == EPI_EVIN || EPI == EPI_ODIN) rs = rsqrtf(ssv[m] * (1.f / 2048.f) + 1e-6f);
;     if constexpr (EPI == EPI_GU) {
;       const f32x4 gv = a[m][0] * rs, uv = a[m][1] * rs;
;       const int hc = (cbase >> 1) + fq * 4;
;       u32x2 o = {cvtpk(silu_f(gv[0]) * uv[0], silu_f(gv[1]) * uv[1]), cvtpk(silu_f(gv[2]) * uv[2], silu_f(gv[3]) * uv[3])};
;       *reinterpret_cast<u32x2*>(G.d0 + (size_t)(row - G.row0) * DFF + hc) = o;
;     } else {
; #pragma unroll
;       for (int n = 0; n < 2; ++n) {
;         const f32x4 v = a[m][n] * rs;
;         const int col = cbase + n * 16 + fq * 4;
;         if constexpr (EPI == EPI_POOL) {
;           const int cg_ = G.aux * 256 + col;
;           f32x4 sc = *reinterpret_cast<const f32x4*>(G.c0 + cg_);
;           u32x2 o = {cvtpk(v[0] * sc[0], v[1] * sc[1]), cvtpk(v[2] * sc[2], v[3] * sc[3])};
;           *reinterpret_cast<u32x2*>(G.d0 + (size_t)row * 1024 + cg_) = o;
;         } else if constexpr (EPI == EPI_EVIN) {
;           u32x2 o = {cvtpk(v[0], v[1]), cvtpk(v[2], v[3])};
;           u16* dp;
;           if (tn < 4) dp = G.d0 + (size_t)row * 1024 + col;
;           else if (tn < 8) dp = G.d1 + (size_t)row * 1024 + (col - 1024);
;           else if (tn == 8) dp = G.d2 + (size_t)row * 256 + (col - 2048);
;           else dp = G.d3 + (size_t)row * 256 + (col - 2304);
;           *reinterpret_cast<u32x2*>(dp) = o;
.Lmy_ev_p11:
	v_lshlrev_b32_e32 v132, 11, v129
	v_lshl_add_u32 v132, v131, 1, v132
	v_add_u32_e32 v132, s7, v132
	v_pk_mul_f32 v[124:125], v[154:155], v[124:125] op_sel_hi:[0,1]
	v_pk_mul_f32 v[120:121], v[154:155], v[120:121] op_sel_hi:[0,1]
	v_pk_mul_f32 v[126:127], v[154:155], v[126:127] op_sel_hi:[0,1]
	v_pk_mul_f32 v[122:123], v[154:155], v[122:123] op_sel_hi:[0,1]
	v_cvt_pk_bf16_f32 v170, v124, v125
	v_cvt_pk_bf16_f32 v172, v120, v121
	v_cvt_pk_bf16_f32 v171, v126, v127
	v_cvt_pk_bf16_f32 v173, v122, v123
	v_mov_b32_e32 v178, v132
	v_add_u32_e32 v179, 0x20, v132
	global_store_dwordx2 v178, v[170:171], s[8:9]
	global_store_dwordx2 v179, v[172:173], s[8:9]
	v_pk_mul_f32 v[116:117], v[156:157], v[116:117] op_sel_hi:[0,1]
	v_pk_mul_f32 v[112:113], v[156:157], v[112:113] op_sel_hi:[0,1]
	v_pk_mul_f32 v[118:119], v[156:157], v[118:119] op_sel_hi:[0,1]
	v_pk_mul_f32 v[114:115], v[156:157], v[114:115] op_sel_hi:[0,1]
	v_cvt_pk_bf16_f32 v174, v116, v117
	v_cvt_pk_bf16_f32 v176, v112, v113
	v_cvt_pk_bf16_f32 v175, v118, v119
	v_cvt_pk_bf16_f32 v177, v114, v115
	v_add_u32_e32 v182, 0x8000, v132
	v_add_u32_e32 v183, 0x8020, v132
	global_store_dwordx2 v182, v[174:175], s[8:9]
	global_store_dwordx2 v183, v[176:177], s[8:9]
	v_pk_mul_f32 v[108:109], v[158:159], v[108:109] op_sel_hi:[0,1]
	v_pk_mul_f32 v[104:105], v[158:159], v[104:105] op_sel_hi:[0,1]
	v_pk_mul_f32 v[110:111], v[158:159], v[110:111] op_sel_hi:[0,1]
	v_pk_mul_f32 v[106:107], v[158:159], v[106:107] op_sel_hi:[0,1]
	v_cvt_pk_bf16_f32 v170, v108, v109
	v_cvt_pk_bf16_f32 v172, v104, v105
	v_cvt_pk_bf16_f32 v171, v110, v111
	v_cvt_pk_bf16_f32 v173, v106, v107
	v_add_u32_e32 v178, 0x10000, v132
	v_add_u32_e32 v179, 0x10020, v132
	global_store_dwordx2 v178, v[170:171], s[8:9]
	global_store_dwordx2 v179, v[172:173], s[8:9]
	v_pk_mul_f32 v[100:101], v[160:161], v[100:101] op_sel_hi:[0,1]
	v_pk_mul_f32 v[96:97], v[160:161], v[96:97] op_sel_hi:[0,1]
	v_pk_mul_f32 v[102:103], v[160:161], v[102:103] op_sel_hi:[0,1]
	v_pk_mul_f32 v[98:99], v[160:161], v[98:99] op_sel_hi:[0,1]
	v_cvt_pk_bf16_f32 v174, v100, v101
	v_cvt_pk_bf16_f32 v176, v96, v97
	v_cvt_pk_bf16_f32 v175, v102, v103
	v_cvt_pk_bf16_f32 v177, v98, v99
	v_add_u32_e32 v182, 0x18000, v132
	v_add_u32_e32 v183, 0x18020, v132
	global_store_dwordx2 v182, v[174:175], s[8:9]
	global_store_dwordx2 v183, v[176:177], s[8:9]
	v_pk_mul_f32 v[92:93], v[154:155], v[92:93] op_sel_hi:[0,1]
	v_pk_mul_f32 v[88:89], v[154:155], v[88:89] op_sel_hi:[0,1]
	v_pk_mul_f32 v[94:95], v[154:155], v[94:95] op_sel_hi:[0,1]
	v_pk_mul_f32 v[90:91], v[154:155], v[90:91] op_sel_hi:[0,1]
	v_cvt_pk_bf16_f32 v170, v92, v93
	v_cvt_pk_bf16_f32 v172, v88, v89
	v_cvt_pk_bf16_f32 v171, v94, v95
	v_cvt_pk_bf16_f32 v173, v90, v91
	v_add_u32_e32 v178, 0x100, v132
	v_add_u32_e32 v179, 0x120, v132
	global_store_dwordx2 v178, v[170:171], s[8:9]
	global_store_dwordx2 v179, v[172:173], s[8:9]
	v_pk_mul_f32 v[84:85], v[156:157], v[84:85] op_sel_hi:[0,1]
	v_pk_mul_f32 v[80:81], v[156:157], v[80:81] op_sel_hi:[0,1]
	v_pk_mul_f32 v[86:87], v[156:157], v[86:87] op_sel_hi:[0,1]
	v_pk_mul_f32 v[82:83], v[156:157], v[82:83] op_sel_hi:[0,1]
	v_cvt_pk_bf16_f32 v174, v84, v85
	v_cvt_pk_bf16_f32 v176, v80, v81
	v_cvt_pk_bf16_f32 v175, v86, v87
	v_cvt_pk_bf16_f32 v177, v82, v83
	v_add_u32_e32 v182, 0x8100, v132
	v_add_u32_e32 v183, 0x8120, v132
	global_store_dwordx2 v182, v[174:175], s[8:9]
	global_store_dwordx2 v183, v[176:177], s[8:9]
	v_pk_mul_f32 v[76:77], v[158:159], v[76:77] op_sel_hi:[0,1]
	v_pk_mul_f32 v[72:73], v[158:159], v[72:73] op_sel_hi:[0,1]
	v_pk_mul_f32 v[78:79], v[158:159], v[78:79] op_sel_hi:[0,1]
	v_pk_mul_f32 v[74:75], v[158:159], v[74:75] op_sel_hi:[0,1]
	v_cvt_pk_bf16_f32 v170, v76, v77
	v_cvt_pk_bf16_f32 v172, v72, v73
	v_cvt_pk_bf16_f32 v171, v78, v79
	v_cvt_pk_bf16_f32 v173, v74, v75
	v_add_u32_e32 v178, 0x10100, v132
	v_add_u32_e32 v179, 0x10120, v132
	global_store_dwordx2 v178, v[170:171], s[8:9]
	global_store_dwordx2 v179, v[172:173], s[8:9]
	v_pk_mul_f32 v[68:69], v[160:161], v[68:69] op_sel_hi:[0,1]
	v_pk_mul_f32 v[64:65], v[160:161], v[64:65] op_sel_hi:[0,1]
	v_pk_mul_f32 v[70:71], v[160:161], v[70:71] op_sel_hi:[0,1]
	v_pk_mul_f32 v[66:67], v[160:161], v[66:67] op_sel_hi:[0,1]
	v_cvt_pk_bf16_f32 v174, v68, v69
	v_cvt_pk_bf16_f32 v176, v64, v65
	v_cvt_pk_bf16_f32 v175, v70, v71
	v_cvt_pk_bf16_f32 v177, v66, v67
	v_add_u32_e32 v182, 0x18100, v132
	v_add_u32_e32 v183, 0x18120, v132
; __device__ __forceinline__ float silu_f(float x) { return x * __builtin_amdgcn_rcpf(1.f + __builtin_amdgcn_exp2f(-1.4426950408889634f * x)); }
; template <int EPI>
; __device__ __forceinline__ void gemm_epi(const GemmArgs& G, const f32x4 (&a)[4][2], int rbase, int cbase, int fq, const float (&ssv)[4]) {
;   const int tn = cbase >> 8;
; #pragma unroll
;   for (int m = 0; m < 4; ++m) {
;     const int row = rbase + m * 16;
;     float rs = 1.f;
;     if constexpr (EPI == EPI_GU || EPI == EPI_EVIN || EPI == EPI_ODIN) rs = rsqrtf(ssv[m] * (1.f / 2048.f) + 1e-6f);
;     if constexpr (EPI == EPI_GU) {
;       const f32x4 gv = a[m][0] * rs, uv = a[m][1] * rs;
;       const int hc = (cbase >> 1) + fq * 4;
;       u32x2 o = {cvtpk(silu_f(gv[0]) * uv[0], silu_f(gv[1]) * uv[1]), cvtpk(silu_f(gv[2]) * uv[2], silu_f(gv[3]) * uv[3])};
;       *reinterpret_cast<u32x2*>(G.d0 + (size_t)(row - G.row0) * DFF + hc) = o;
;     } else {
; #pragma unroll
;       for (int n = 0; n < 2; ++n) {
;         const f32x4 v = a[m][n] * rs;
;         const int col = cbase + n * 16 + fq * 4;
;         if constexpr (EPI == EPI_POOL) {
;           const int cg_ = G.aux * 256 + col;
;           f32x4 sc = *reinterpret_cast<const f32x4*>(G.c0 + cg_);
;           u32x2 o = {cvtpk(v[0] * sc[0], v[1] * sc[1]), cvtpk(v[2] * sc[2], v[3] * sc[3])};
;           *reinterpret_cast<u32x2*>(G.d0 + (size_t)row * 1024 + cg_) = o;
;         } else if constexpr (EPI == EPI_EVIN) {
;           u32x2 o = {cvtpk(v[0], v[1]), cvtpk(v[2], v[3])};
;           u16* dp;
;           if (tn < 4) dp = G.d0 + (size_t)row * 1024 + col;
;           else if (tn < 8) dp = G.d1 + (size_t)row * 1024 + (col - 1024);
;           else if (tn == 8) dp = G.d2 + (size_t)row * 256 + (col - 2048);
;           else dp = G.d3 + (size_t)row * 256 + (col - 2304);
;           *reinterpret_cast<u32x2*>(dp) = o;
	global_store_dwordx2 v182, v[174:175], s[8:9]
	global_store_dwordx2 v183, v[176:177], s[8:9]
	v_pk_mul_f32 v[60:61], v[162:163], v[60:61] op_sel_hi:[0,1]
	v_pk_mul_f32 v[56:57], v[162:163], v[56:57] op_sel_hi:[0,1]
	v_pk_mul_f32 v[62:63], v[162:163], v[62:63] op_sel_hi:[0,1]
	v_pk_mul_f32 v[58:59], v[162:163], v[58:59] op_sel_hi:[0,1]
	v_cvt_pk_bf16_f32 v170, v60, v61
	v_cvt_pk_bf16_f32 v172, v56, v57
	v_cvt_pk_bf16_f32 v171, v62, v63
	v_cvt_pk_bf16_f32 v173, v58, v59
	v_add_u32_e32 v178, 0x40000, v132
	v_add_u32_e32 v179, 0x40020, v132
	global_store_dwordx2 v178, v[170:171], s[8:9]
	global_store_dwordx2 v179, v[172:173], s[8:9]
	v_pk_mul_f32 v[52:53], v[164:165], v[52:53] op_sel_hi:[0,1]
	v_pk_mul_f32 v[48:49], v[164:165], v[48:49] op_sel_hi:[0,1]
	v_pk_mul_f32 v[54:55], v[164:165], v[54:55] op_sel_hi:[0,1]
	v_pk_mul_f32 v[50:51], v[164:165], v[50:51] op_sel_hi:[0,1]
	v_cvt_pk_bf16_f32 v174, v52, v53
	v_cvt_pk_bf16_f32 v176, v48, v49
	v_cvt_pk_bf16_f32 v175, v54, v55
	v_cvt_pk_bf16_f32 v177, v50, v51
	v_add_u32_e32 v182, 0x48000, v132
	v_add_u32_e32 v183, 0x48020, v132
	global_store_dwordx2 v182, v[174:175], s[8:9]
	global_store_dwordx2 v183, v[176:177], s[8:9]
	v_pk_mul_f32 v[44:45], v[166:167], v[44:45] op_sel_hi:[0,1]
	v_pk_mul_f32 v[40:41], v[166:167], v[40:41] op_sel_hi:[0,1]
	v_pk_mul_f32 v[46:47], v[166:167], v[46:47] op_sel_hi:[0,1]
	v_pk_mul_f32 v[42:43], v[166:167], v[42:43] op_sel_hi:[0,1]
	v_cvt_pk_bf16_f32 v170, v44, v45
	v_cvt_pk_bf16_f32 v172, v40, v41
	v_cvt_pk_bf16_f32 v171, v46, v47
	v_cvt_pk_bf16_f32 v173, v42, v43
	v_add_u32_e32 v178, 0x50000, v132
	v_add_u32_e32 v179, 0x50020, v132
	global_store_dwordx2 v178, v[170:171], s[8:9]
	global_store_dwordx2 v179, v[172:173], s[8:9]
	v_pk_mul_f32 v[36:37], v[168:169], v[36:37] op_sel_hi:[0,1]
	v_pk_mul_f32 v[32:33], v[168:169], v[32:33] op_sel_hi:[0,1]
	v_pk_mul_f32 v[38:39], v[168:169], v[38:39] op_sel_hi:[0,1]
	v_pk_mul_f32 v[34:35], v[168:169], v[34:35] op_sel_hi:[0,1]
	v_cvt_pk_bf16_f32 v174, v36, v37
	v_cvt_pk_bf16_f32 v176, v32, v33
	v_cvt_pk_bf16_f32 v175, v38, v39
	v_cvt_pk_bf16_f32 v177, v34, v35
	v_add_u32_e32 v182, 0x58000, v132
	v_add_u32_e32 v183, 0x58020, v132
	global_store_dwordx2 v182, v[174:175], s[8:9]
	global_store_dwordx2 v183, v[176:177], s[8:9]
	v_pk_mul_f32 v[28:29], v[162:163], v[28:29] op_sel_hi:[0,1]
	v_pk_mul_f32 v[24:25], v[162:163], v[24:25] op_sel_hi:[0,1]
	v_pk_mul_f32 v[30:31], v[162:163], v[30:31] op_sel_hi:[0,1]
	v_pk_mul_f32 v[26:27], v[162:163], v[26:27] op_sel_hi:[0,1]
	v_cvt_pk_bf16_f32 v170, v28, v29
	v_cvt_pk_bf16_f32 v172, v24, v25
	v_cvt_pk_bf16_f32 v171, v30, v31
	v_cvt_pk_bf16_f32 v173, v26, v27
	v_add_u32_e32 v178, 0x40100, v132
	v_add_u32_e32 v179, 0x40120, v132
	global_store_dwordx2 v178, v[170:171], s[8:9]
	global_store_dwordx2 v179, v[172:173], s[8:9]
	v_pk_mul_f32 v[20:21], v[164:165], v[20:21] op_sel_hi:[0,1]
	v_pk_mul_f32 v[16:17], v[164:165], v[16:17] op_sel_hi:[0,1]
	v_pk_mul_f32 v[22:23], v[164:165], v[22:23] op_sel_hi:[0,1]
	v_pk_mul_f32 v[18:19], v[164:165], v[18:19] op_sel_hi:[0,1]
	v_cvt_pk_bf16_f32 v174, v20, v21
	v_cvt_pk_bf16_f32 v176, v16, v17
	v_cvt_pk_bf16_f32 v175, v22, v23
	v_cvt_pk_bf16_f32 v177, v18, v19
	v_add_u32_e32 v182, 0x48100, v132
	v_add_u32_e32 v183, 0x48120, v132
	global_store_dwordx2 v182, v[174:175], s[8:9]
	global_store_dwordx2 v183, v[176:177], s[8:9]
	v_pk_mul_f32 v[12:13], v[166:167], v[12:13] op_sel_hi:[0,1]
	v_pk_mul_f32 v[8:9], v[166:167], v[8:9] op_sel_hi:[0,1]
	v_pk_mul_f32 v[14:15], v[166:167], v[14:15] op_sel_hi:[0,1]
	v_pk_mul_f32 v[10:11], v[166:167], v[10:11] op_sel_hi:[0,1]
	v_cvt_pk_bf16_f32 v170, v12, v13
	v_cvt_pk_bf16_f32 v172, v8, v9
	v_cvt_pk_bf16_f32 v171, v14, v15
	v_cvt_pk_bf16_f32 v173, v10, v11
	v_add_u32_e32 v178, 0x50100, v132
	v_add_u32_e32 v179, 0x50120, v132
	global_store_dwordx2 v178, v[170:171], s[8:9]
	global_store_dwordx2 v179, v[172:173], s[8:9]
	v_pk_mul_f32 v[4:5], v[168:169], v[4:5] op_sel_hi:[0,1]
	v_pk_mul_f32 v[0:1], v[168:169], v[0:1] op_sel_hi:[0,1]
	v_pk_mul_f32 v[6:7], v[168:169], v[6:7] op_sel_hi:[0,1]
	v_pk_mul_f32 v[2:3], v[168:169], v[2:3] op_sel_hi:[0,1]
	v_cvt_pk_bf16_f32 v174, v4, v5
	v_cvt_pk_bf16_f32 v176, v0, v1
	v_cvt_pk_bf16_f32 v175, v6, v7
	v_cvt_pk_bf16_f32 v177, v2, v3
	v_add_u32_e32 v182, 0x58100, v132
	v_add_u32_e32 v183, 0x58120, v132
	global_store_dwordx2 v182, v[174:175], s[8:9]
	global_store_dwordx2 v183, v[176:177], s[8:9]
	s_branch .Lmy_ev_done
